# attn loop: unswapped V LDS rows so P needs no half-swaps (-8 permlane/tile); scalar fast path when no row max grows past threshold
# speedup vs baseline: 1.0202x; 1.0047x over previous
; __device__ __forceinline__ int v_rd_base(int lane) { return ((lane & 3) << 3) | (((lane >> 2) & 3) << 6) | (((lane >> 4) & 1) << 5) | (((lane >> 5) & 1) << 8); }
; #define LBAR() do { asm volatile("s_waitcnt lgkmcnt(0)" ::: "memory"); __builtin_amdgcn_s_barrier(); asm volatile("" ::: "memory"); } while (0)
; __device__ __forceinline__ int v_st(int k, int c) { const int kk = (k & ~0xC) | ((k & 4) << 1) | ((k & 8) >> 1); return ((kk >> 3) * 4 + (c >> 5)) * 512 + ((kk & 7) * 32 + (c & 31)) * 2; }
; __device__ __forceinline__ void attn_unit(const bf16_t* __restrict__ Qb, const bf16_t* __restrict__ Kn, const bf16_t* __restrict__ Vh, const bf16_t* __restrict__ Kr,
;                                           bf16_t* GO, int seq, char* lds, const int tid) {
;   const int wid = tid >> 6, lane = tid & 63, r32 = lane & 31, hi = lane >> 5;
;   char* V_lds = lds; char* K_lds = lds + 3 * SHM_V;
;   float* ws = (float*)(lds + 3 * SHM_V + 3 * SHM_K) + wid * 64; float* li_l = ws; float* al_l = ws + 32;
;   if (wid < 4) __builtin_amdgcn_s_setprio(2); else __builtin_amdgcn_s_setprio(0);
;   float m_reg = -1e30f, l_reg = 0; f32x16 o[4] = {}; bf16x8 qr[8];
;   char* qrl = lds + 3 * SHM_V + 3 * SHM_K + NW * 64 * 4 + wid * 4096 + r32 * 128;
;   const bf16_t* Qw = Qb + (long)(wid * QBLK + r32) * LDQ + hi * 8;
; #pragma unroll
;   for (int d0 = 0; d0 < 8; ++d0) qr[d0] = *reinterpret_cast<const bf16x8*>(Qw + d0 * 16);
; #pragma unroll
;   for (int d0 = 8; d0 < 12; ++d0) *reinterpret_cast<bf16x8*>(qrl + (((2 * (d0 - 8) + hi) ^ ((r32 >> 1) & 7)) << 4)) = *reinterpret_cast<const bf16x8*>(Qw + d0 * 16);
;   const int sr = tid >> 4, sc = (tid & 15) * 8, vst0 = v_st(sr, sc), vst1 = v_st(32 + sr, sc);
;   const int rr = tid >> 3, rc = (tid & 7) * 8;
;   const int vb0 = (int)(uintptr_t)V_lds + v_rd_base(lane);
;   const unsigned offkv = (unsigned)(sr * LDKV + sc) * 2u, offkr = (unsigned)(rr * LDKR + rc) * 2u;
;   struct { bf16x8 vs0, vs1, ks0, ks1, kr; } sr_[1];
;     ...
;   f32x16 pA0, pA1, pB0, pB1; float mnA, mnB, alA, alB; bf16x8 pa0, pa1, pa2, pa3; const int NT = seq / KVBLK;
;     ...
;   SLOAD(0, 0); SWRITE(0, 0); SLOAD(0, KVBLK); LBAR();
;   qkt(pA0, pA1, K_lds, qr, qrl, r32, hi); partialSM(pA0, pA1, m_reg, mnA, alA);
;   SWRITE(1, 0); if (2 < NT) SLOAD(0, 2 * KVBLK); LBAR();
.Lattn_prio_done:
	s_add_u32 s55, s40, s34
	s_addc_u32 s56, s41, s35
	s_sub_i32 s18, s54, s20
	s_cmp_ge_u32 s54, s20
	s_cselect_b32 s18, s18, s54
	s_xor_b32 s18, s18, s51
	s_sub_i32 s18, s18, s51
	s_ashr_i32 s34, s53, 3
	s_ashr_i32 s35, s34, 31
	s_ashr_i32 s19, s18, 31
	s_and_b32 s51, s53, 7
	s_lshl_b64 s[40:41], s[34:35], s44
	s_lshl_b64 s[18:19], s[18:19], 8
	s_add_u32 s69, s40, s18
	s_addc_u32 s72, s41, s19
	s_add_u32 s53, s30, s28
	s_mul_i32 s18, s72, 0xc00
	s_mul_hi_u32 s19, s69, 0xc00
	s_addc_u32 s54, s31, s29
	s_add_i32 s19, s19, s18
	s_mul_i32 s18, s69, 0xc00
	s_add_u32 s18, s55, s18
	s_addc_u32 s19, s56, s19
	s_mul_i32 s34, s51, 0x180
	s_add_u32 s18, s18, s34
	s_addc_u32 s19, s19, 0
	v_and_b32_e32 v170, 31, v32
	v_lshlrev_b32_e32 v172, 5, v0
	v_bfe_u32 v171, v32, 5, 1
	v_or_b32_e32 v1, v172, v170
	v_mov_b64_e32 v[2:3], s[18:19]
	v_mad_i64_i32 v[2:3], s[18:19], v1, s49, v[2:3]
	v_lshlrev_b32_e32 v164, 4, v171
	v_mov_b32_e32 v165, v193
	v_lshl_add_u64 v[30:31], v[2:3], 0, v[164:165]
	global_load_dwordx4 v[2:5], v[30:31], off offset:256
	global_load_dwordx4 v[6:9], v[30:31], off offset:288
	s_lshl_b64 s[34:35], s[40:41], 12
	s_add_u32 s19, s53, s34
	s_addc_u32 s53, s54, s35
	s_lshl_b32 s18, s51, 9
	s_add_u32 s54, s19, s18
	s_addc_u32 s55, s53, 0
	v_lshlrev_b32_e32 v42, 3, v33
	s_add_u32 s40, s40, s42
	v_and_b32_e32 v18, 0x78, v42
	s_addc_u32 s41, s41, 0
	v_ashrrev_i32_e32 v1, 4, v33
	v_lshlrev_b32_e32 v43, 1, v18
	s_lshl_b64 s[56:57], s[40:41], 7
	s_add_i32 s19, 0, 0x1e000
	s_add_i32 s41, 0, 0x1e800
	v_lshl_or_b32 v68, v1, 12, v43
	v_mov_b32_e32 v69, v193
	v_and_b32_e32 v18, 56, v42
	s_cmp_lg_u32 0, -1
	v_lshl_add_u64 v[72:73], s[54:55], 0, v[68:69]
	v_ashrrev_i32_e32 v44, 3, v33
	s_cselect_b32 s40, 0, 0
	v_lshlrev_b32_e32 v192, 1, v18
	v_add_co_u32_e32 v34, vcc, s79, v72
	s_waitcnt lgkmcnt(0)
	s_add_u32 s38, s38, s56
	v_addc_co_u32_e32 v35, vcc, 0, v73, vcc
	v_lshl_or_b32 v38, v44, 7, v192
	v_mov_b32_e32 v39, v193
	s_addc_u32 s39, s39, s57
	global_load_dwordx4 v[10:13], v[30:31], off offset:320
	global_load_dwordx4 v[14:17], v[30:31], off offset:352
	global_load_dwordx4 v[18:21], v68, s[54:55] offset:256
	global_load_dwordx4 v[22:25], v[34:35], off offset:256
	global_load_dwordx4 v[26:29], v68, s[54:55]
	s_nop 0
	global_load_dwordx4 v[34:37], v[34:35], off
	v_lshl_add_u64 v[70:71], s[38:39], 0, v[38:39]
	s_mov_b32 s38, 0x13000000
	v_add_co_u32_e32 v38, vcc, s38, v70
	v_lshrrev_b32_e32 v45, 1, v33
	s_nop 0
	v_addc_co_u32_e32 v39, vcc, 0, v71, vcc
	global_load_dwordx4 v[38:41], v[38:39], off
	s_nop 0
	global_load_dwordx4 v[124:127], v[30:31], off
	global_load_dwordx4 v[120:123], v[30:31], off offset:32
	global_load_dwordx4 v[116:119], v[30:31], off offset:64
	global_load_dwordx4 v[112:115], v[30:31], off offset:96
	global_load_dwordx4 v[108:111], v[30:31], off offset:128
	global_load_dwordx4 v[104:107], v[30:31], off offset:160
	global_load_dwordx4 v[100:103], v[30:31], off offset:192
	global_load_dwordx4 v[96:99], v[30:31], off offset:224
	v_bfe_u32 v46, v33, 1, 3
	v_bitop3_b32 v47, v45, v171, 7 bitop3:0x6c
	v_lshl_add_u32 v165, v0, 12, s41
	v_bitop3_b32 v48, v171, v46, 2 bitop3:0x36
	v_lshlrev_b32_e32 v47, 4, v47
	v_lshl_add_u32 v0, v170, 7, v165
	v_lshlrev_b32_e32 v48, 4, v48
	v_add_u32_e32 v182, v0, v47
	v_add_u32_e32 v181, v0, v48
	s_mov_b32 s38, 0x13002000
	v_mul_u32_u24_e32 v47, 0x180, v170
	v_or_b32_e32 v80, 0x120, v164
	v_and_b32_e32 v174, 63, v32
	v_lshlrev_b32_e32 v79, 4, v32
	s_mov_b32 s53, s52
	s_mov_b32 s54, s52
	s_mov_b32 s55, s52
	s_waitcnt vmcnt(16)
	ds_write_b128 v182, v[2:5]
	s_waitcnt vmcnt(15)
	ds_write_b128 v181, v[6:9]
	v_bitop3_b32 v2, v171, v46, 4 bitop3:0x36
	v_lshlrev_b32_e32 v2, 4, v2
	v_add_u32_e32 v179, v0, v2
	v_bitop3_b32 v2, v171, v46, 6 bitop3:0x36
	v_lshlrev_b32_e32 v2, 4, v2
	v_add_u32_e32 v177, v0, v2
	v_and_b32_e32 v0, 0xfffff8, v1
	v_lshlrev_b32_e32 v2, 1, v1
	v_and_or_b32 v0, v2, 0, v0
	v_lshrrev_b32_e32 v2, 1, v1
	v_lshrrev_b32_e32 v0, 1, v0
	v_bfe_u32 v3, v42, 5, 2
	v_and_b32_e32 v4, 3, v1
	v_or_b32_e32 v0, v0, v3
	v_and_b32_e32 v2, 7, v1
	v_lshlrev_b32_e32 v0, 9, v0
	v_lshlrev_b32_e32 v2, 6, v2
	v_and_b32_e32 v4, 48, v43
	v_or3_b32 v183, v0, v2, v4
	v_add_u32_e32 v0, 32, v1
	v_and_b32_e32 v5, 0xfffff8, v0
	v_lshlrev_b32_e32 v0, 1, v0
	v_and_or_b32 v0, v0, 0, v5
	v_lshrrev_b32_e32 v0, 1, v0
	v_or_b32_e32 v0, v0, v3
	v_lshlrev_b32_e32 v0, 9, v0
	v_or3_b32 v184, v0, v2, v4
	v_mul_lo_u32 v0, v1, s8
	v_and_b32_e32 v1, 0x70, v45
	v_xad_u32 v185, v43, v1, v0
	v_add_u32_e32 v82, 0, v183
	v_add_u32_e32 v83, 0, v184
	v_add_u32_e32 v0, 0, v185
	s_waitcnt vmcnt(14)
	ds_write_b128 v179, v[10:13]
	s_waitcnt vmcnt(13)
	ds_write_b128 v177, v[14:17]
	s_waitcnt vmcnt(12)
	ds_write_b128 v82, v[18:21]
	s_waitcnt vmcnt(11)
	ds_write_b128 v83, v[22:25]
	s_waitcnt vmcnt(10)
	ds_write_b128 v0, v[26:29] offset:49152
	s_waitcnt vmcnt(9)
	ds_write_b128 v0, v[34:37] offset:61440
	v_mul_lo_u32 v0, v44, s8
	v_or_b32_e32 v1, 0x100, v192
	v_and_b32_e32 v2, 0x70, v33
	v_xad_u32 v186, v1, v2, v0
	v_add_u32_e32 v0, 0, v186
	s_waitcnt vmcnt(8)
	ds_write_b128 v0, v[38:41] offset:49152
	v_add_co_u32_e32 v0, vcc, s84, v72
	v_or_b32_e32 v34, 32, v164
	s_nop 0
	v_addc_co_u32_e32 v1, vcc, 0, v73, vcc
	v_add_co_u32_e32 v2, vcc, s85, v72
	v_lshlrev_b32_e32 v46, 4, v46
	s_nop 0
	v_addc_co_u32_e32 v3, vcc, 0, v73, vcc
	global_load_dwordx4 v[48:51], v[0:1], off offset:256
	global_load_dwordx4 v[52:55], v[0:1], off
	global_load_dwordx4 v[60:63], v[2:3], off offset:256
	global_load_dwordx4 v[56:59], v[2:3], off
	v_add_co_u32_e32 v0, vcc, s38, v70
	v_or_b32_e32 v42, 0x100, v164
	s_nop 0
	v_addc_co_u32_e32 v1, vcc, 0, v71, vcc
	global_load_dwordx4 v[64:67], v[0:1], off
	v_lshlrev_b32_e32 v0, 3, v32
	v_and_b32_e32 v78, 0x70, v0
	v_bitop3_b32 v199, v164, v47, v78 bitop3:0xde
	s_waitcnt lgkmcnt(0)
	s_barrier
; __device__ __forceinline__ void qkt(f32x16& p0, f32x16& p1, const char* Ks, const bf16x8* qr, const char* qrl, int r32, int hi) {
;   p0 = f32x16{}; p1 = f32x16{};
; #pragma unroll
;   for (int d0 = 0; d0 < 8; ++d0) { int cb = (d0 * 16 + hi * 8) * 2;
;     bf16x8 b0 = *reinterpret_cast<const bf16x8*>(Ks + KSWZ(r32, cb));
;     bf16x8 b1 = *reinterpret_cast<const bf16x8*>(Ks + KSWZ(32 + r32, cb));
;     p0 = __builtin_amdgcn_mfma_f32_32x32x16_bf16(b0, qr[d0], p0, 0, 0, 0);
;     p1 = __builtin_amdgcn_mfma_f32_32x32x16_bf16(b1, qr[d0], p1, 0, 0, 0); }
; #pragma unroll
;   for (int d0 = 8; d0 < 12; ++d0) { int cb = (d0 * 16 + hi * 8) * 2;
;     bf16x8 b0 = *reinterpret_cast<const bf16x8*>(Ks + KSWZ(r32, cb));
;     bf16x8 b1 = *reinterpret_cast<const bf16x8*>(Ks + KSWZ(32 + r32, cb));
;     bf16x8 qf = *reinterpret_cast<const bf16x8*>(qrl + (((2 * (d0 - 8) + hi) ^ ((r32 >> 1) & 7)) << 4));
;     p0 = __builtin_amdgcn_mfma_f32_32x32x16_bf16(b0, qf, p0, 0, 0, 0);
;     p1 = __builtin_amdgcn_mfma_f32_32x32x16_bf16(b1, qf, p1, 0, 0, 0); }
; }
	v_add_u32_e32 v4, 0, v199
	ds_read_b128 v[0:3], v4 offset:49152
	ds_read_b128 v[16:19], v4 offset:61440
	s_waitcnt vmcnt(12) lgkmcnt(1)
	v_mfma_f32_32x32x16_bf16 v[0:15], v[0:3], v[124:127], 0
	v_bitop3_b32 v205, v34, v47, v78 bitop3:0xde
	v_add_u32_e32 v38, 0, v205
	ds_read_b128 v[34:37], v38 offset:49152
	ds_read_b128 v[38:41], v38 offset:61440
	v_xad_u32 v191, v42, v46, v47
	v_and_b32_e32 v33, 0x3fffffc0, v33
	v_xad_u32 v202, v42, v78, v47
	v_lshl_add_u32 v173, v33, 2, s19
	s_waitcnt lgkmcnt(2)
	v_mfma_f32_32x32x16_bf16 v[16:31], v[16:19], v[124:127], 0
	v_add_u32_e32 v33, 0, v202
	v_xad_u32 v198, v80, v46, v47
	v_xad_u32 v201, v80, v78, v47
	v_lshlrev_b32_e32 v32, 1, v32
	v_and_b32_e32 v32, 32, v32
	s_mov_b32 s19, 0x13004000
	s_mov_b32 s56, s52
	s_waitcnt vmcnt(11) lgkmcnt(1)
	v_mfma_f32_32x32x16_bf16 v[0:15], v[34:37], v[120:123], v[0:15]
	v_or_b32_e32 v34, 64, v164
	v_bitop3_b32 v206, v34, v47, v78 bitop3:0xde
	s_mov_b32 s57, s52
	s_mov_b32 s58, s52
	s_mov_b32 s59, s52
	s_mov_b32 s60, s52
	s_mov_b32 s61, s52
	s_waitcnt lgkmcnt(0)
	v_mfma_f32_32x32x16_bf16 v[16:31], v[38:41], v[120:123], v[16:31]
	v_add_u32_e32 v38, 0, v206
	ds_read_b128 v[34:37], v38 offset:49152
	ds_read_b128 v[38:41], v38 offset:61440
	s_mov_b32 s62, s52
	s_mov_b32 s63, s52
	s_mov_b32 s64, s52
	s_mov_b32 s65, s52
	s_mov_b32 s66, s52
	s_waitcnt vmcnt(10) lgkmcnt(1)
	v_mfma_f32_32x32x16_bf16 v[0:15], v[34:37], v[116:119], v[0:15]
	v_or_b32_e32 v34, 0x60, v164
	v_bitop3_b32 v208, v34, v47, v78 bitop3:0xde
	s_mov_b32 s67, s52
	s_mov_b32 s73, 2
	s_mov_b32 s76, 1
	v_cmp_gt_u32_e64 s[38:39], 32, v174
	v_lshl_add_u32 v175, v170, 2, v173
	s_waitcnt lgkmcnt(0)
	v_mfma_f32_32x32x16_bf16 v[16:31], v[38:41], v[116:119], v[16:31]
	v_add_u32_e32 v38, 0, v208
	ds_read_b128 v[34:37], v38 offset:49152
	ds_read_b128 v[38:41], v38 offset:61440
	v_mov_b32_e32 v176, 0
	s_waitcnt vmcnt(9) lgkmcnt(1)
	v_mfma_f32_32x32x16_bf16 v[0:15], v[34:37], v[112:115], v[0:15]
	v_or_b32_e32 v34, 0x80, v164
	v_xad_u32 v207, v34, v78, v47
	s_waitcnt lgkmcnt(0)
	v_mfma_f32_32x32x16_bf16 v[16:31], v[38:41], v[112:115], v[16:31]
	v_add_u32_e32 v38, 0, v207
	ds_read_b128 v[34:37], v38 offset:49152
	ds_read_b128 v[38:41], v38 offset:61440
	s_waitcnt vmcnt(8) lgkmcnt(1)
	v_mfma_f32_32x32x16_bf16 v[0:15], v[34:37], v[108:111], v[0:15]
	v_or_b32_e32 v34, 0xa0, v164
	v_xad_u32 v204, v34, v78, v47
	s_waitcnt lgkmcnt(0)
	v_mfma_f32_32x32x16_bf16 v[16:31], v[38:41], v[108:111], v[16:31]
	v_add_u32_e32 v38, 0, v204
	ds_read_b128 v[34:37], v38 offset:49152
	ds_read_b128 v[38:41], v38 offset:61440
	s_waitcnt vmcnt(7) lgkmcnt(1)
	v_mfma_f32_32x32x16_bf16 v[0:15], v[34:37], v[104:107], v[0:15]
	v_or_b32_e32 v34, 0xc0, v164
	v_xad_u32 v203, v34, v78, v47
	s_waitcnt lgkmcnt(0)
	v_mfma_f32_32x32x16_bf16 v[16:31], v[38:41], v[104:107], v[16:31]
	v_add_u32_e32 v38, 0, v203
	ds_read_b128 v[34:37], v38 offset:49152
	ds_read_b128 v[38:41], v38 offset:61440
	s_waitcnt vmcnt(6) lgkmcnt(1)
	v_mfma_f32_32x32x16_bf16 v[0:15], v[34:37], v[100:103], v[0:15]
	v_or_b32_e32 v34, 0xe0, v164
	v_xad_u32 v200, v34, v78, v47
	s_waitcnt lgkmcnt(0)
	v_mfma_f32_32x32x16_bf16 v[16:31], v[38:41], v[100:103], v[16:31]
	v_add_u32_e32 v38, 0, v200
	ds_read_b128 v[34:37], v38 offset:49152
	ds_read_b128 v[38:41], v38 offset:61440
	s_waitcnt vmcnt(5) lgkmcnt(1)
	v_mfma_f32_32x32x16_bf16 v[0:15], v[34:37], v[96:99], v[0:15]
	v_add_u32_e32 v34, 0, v191
	ds_read_b128 v[34:37], v34 offset:49152
	s_waitcnt lgkmcnt(1)
	v_mfma_f32_32x32x16_bf16 v[16:31], v[38:41], v[96:99], v[16:31]
	ds_read_b128 v[38:41], v182
	ds_read_b128 v[42:45], v33 offset:61440
	ds_read_b128 v[74:77], v181
	v_lshlrev_b32_e32 v33, 3, v174
	s_waitcnt lgkmcnt(2)
	v_mfma_f32_32x32x16_bf16 v[0:15], v[34:37], v[38:41], v[0:15]
	v_add_u32_e32 v34, 0, v198
	ds_read_b128 v[34:37], v34 offset:49152
	s_waitcnt lgkmcnt(2)
	v_mfma_f32_32x32x16_bf16 v[16:31], v[42:45], v[38:41], v[16:31]
	v_and_b32_e32 v38, 0xc0, v79
	v_and_or_b32 v42, v33, 24, v38
	v_add_u32_e32 v38, 0, v201
	ds_read_b128 v[38:41], v38 offset:61440
	v_and_b32_e32 v33, 0x100, v33
	v_or3_b32 v32, v42, v32, v33
	v_or_b32_e32 v42, 0x140, v164
	v_xad_u32 v187, v42, v46, v47
	v_add_u32_e32 v178, s40, v32
	v_add_u32_e32 v32, 0, v187
	s_waitcnt lgkmcnt(1)
	v_mfma_f32_32x32x16_bf16 v[0:15], v[34:37], v[74:77], v[0:15]
	ds_read_b128 v[32:35], v32 offset:49152
	v_or_b32_e32 v44, 0x160, v164
	v_xad_u32 v189, v42, v78, v47
	v_xad_u32 v188, v44, v46, v47
	v_xad_u32 v190, v44, v78, v47
	s_mov_b64 s[40:41], 0x13008000
	v_lshl_add_u64 v[166:167], v[70:71], 0, s[40:41]
	s_waitcnt lgkmcnt(1)
	v_mfma_f32_32x32x16_bf16 v[16:31], v[38:41], v[74:77], v[16:31]
	ds_read_b128 v[36:39], v179
	v_add_u32_e32 v40, 0, v189
	ds_read_b128 v[40:43], v40 offset:61440
	ds_read_b128 v[74:77], v177
	s_waitcnt lgkmcnt(2)
	v_mfma_f32_32x32x16_bf16 v[0:15], v[32:35], v[36:39], v[0:15]
	v_add_u32_e32 v32, 0, v188
	ds_read_b128 v[32:35], v32 offset:49152
	s_waitcnt lgkmcnt(2)
	v_mfma_f32_32x32x16_bf16 v[16:31], v[40:43], v[36:39], v[16:31]
	v_add_u32_e32 v36, 0, v190
	ds_read_b128 v[78:81], v36 offset:61440
	s_waitcnt lgkmcnt(1)
	v_mfma_f32_32x32x16_bf16 v[0:15], v[32:35], v[74:77], v[0:15]
	v_mov_b64_e32 v[32:33], s[52:53]
	v_mov_b64_e32 v[46:47], s[66:67]
	v_mov_b64_e32 v[34:35], s[54:55]
	v_mov_b64_e32 v[36:37], s[56:57]
	v_mov_b64_e32 v[38:39], s[58:59]
	v_mov_b64_e32 v[40:41], s[60:61]
	v_mov_b64_e32 v[42:43], s[62:63]
	s_waitcnt lgkmcnt(0)
; #define LBAR() do { asm volatile("s_waitcnt lgkmcnt(0)" ::: "memory"); __builtin_amdgcn_s_barrier(); asm volatile("" ::: "memory"); } while (0)
; __device__ __forceinline__ void partialSM(f32x16& p0, f32x16& p1, float& m_reg, float& mn, float& alpha) {
;   constexpr float C = SCALE * 1.4426950408889634f;
;   float pmax = p0[0];
; #pragma unroll
;   for (int r = 1; r < 16; ++r) pmax = fmaxf(pmax, p0[r]);
; #pragma unroll
;   for (int r = 0; r < 16; ++r) pmax = fmaxf(pmax, p1[r]);
;   { auto rr = __builtin_amdgcn_permlane32_swap(__float_as_uint(pmax), __float_as_uint(pmax), false, false);
;     pmax = fmaxf(__uint_as_float(rr[0]), __uint_as_float(rr[1])); }
;   if (__builtin_expect(__all(pmax - m_reg <= THR / SCALE), 1)) { mn = m_reg; alpha = 1.f; }
;   else { mn = fmaxf(m_reg, pmax); alpha = __builtin_amdgcn_exp2f((m_reg - mn) * C); m_reg = mn; }
;   float mnC = -mn * C;
; #pragma unroll
;   for (int r = 0; r < 16; ++r) p0[r] = fmaf(p0[r], C, mnC);
; #pragma unroll
;   for (int r = 0; r < 16; ++r) p1[r] = fmaf(p1[r], C, mnC);
; #pragma unroll
;   for (int r = 0; r < 16; ++r) p0[r] = __builtin_amdgcn_exp2f(p0[r]);
; }
; __device__ __forceinline__ void attn_unit(const bf16_t* __restrict__ Qb, const bf16_t* __restrict__ Kn, const bf16_t* __restrict__ Vh, const bf16_t* __restrict__ Kr,
;                                           bf16_t* GO, int seq, char* lds, const int tid) {
;     ...
;   SWRITE(1, 0); if (2 < NT) SLOAD(0, 2 * KVBLK); LBAR();
	v_mfma_f32_32x32x16_bf16 v[16:31], v[78:81], v[74:77], v[16:31]
	s_nop 2
	v_max_f32_e32 v74, v1, v1
	v_max_f32_e32 v75, v0, v0
	v_max_f32_e32 v74, v75, v74
	v_max3_f32 v74, v74, v2, v3
	v_max3_f32 v74, v74, v4, v5
	v_max3_f32 v74, v74, v6, v7
	v_max3_f32 v74, v74, v8, v9
	v_max3_f32 v74, v74, v10, v11
	v_max3_f32 v74, v74, v12, v13
	v_max3_f32 v74, v74, v14, v15
	v_max3_f32 v74, v74, v16, v17
	v_max3_f32 v74, v74, v18, v19
	v_max3_f32 v74, v74, v20, v21
	v_max3_f32 v74, v74, v22, v23
	v_max3_f32 v74, v74, v24, v25
	v_max3_f32 v74, v74, v26, v27
	v_max3_f32 v74, v74, v28, v29
	v_max3_f32 v76, v74, v30, v31
	v_mov_b32_e32 v74, v76
	s_nop 1
	v_permlane32_swap_b32_e32 v76, v74
	v_max_f32_e32 v77, v74, v74
	v_add_co_u32_e32 v74, vcc, s19, v70
	s_add_i32 s19, 0, 0x12000
	s_nop 0
	v_addc_co_u32_e32 v75, vcc, 0, v71, vcc
	global_load_dwordx4 v[128:131], v[74:75], off
	v_add_co_u32_e32 v74, vcc, s14, v72
	v_mov_b64_e32 v[44:45], s[64:65]
	s_nop 0
	v_addc_co_u32_e32 v75, vcc, 0, v73, vcc
	v_add_co_u32_e32 v72, vcc, s9, v72
	s_nop 1
	v_addc_co_u32_e32 v73, vcc, 0, v73, vcc
	global_load_dwordx4 v[132:135], v[74:75], off
	global_load_dwordx4 v[144:147], v[74:75], off offset:256
	global_load_dwordx4 v[136:139], v[72:73], off
	global_load_dwordx4 v[140:143], v[72:73], off offset:256
	v_max_f32_e32 v72, v76, v76
	v_max_f32_e32 v72, v72, v77
	v_add_f32_e32 v73, 0x7149f2ca, v72
	v_cmp_ge_f32_e32 vcc, s15, v73
	s_waitcnt vmcnt(9)
	ds_write_b128 v82, v[48:51] offset:16384
	s_waitcnt vmcnt(7)
	ds_write_b128 v83, v[60:63] offset:16384
	v_add_u32_e32 v48, s19, v185
	ds_write_b128 v48, v[52:55]
	s_waitcnt vmcnt(6)
	ds_write_b128 v48, v[56:59] offset:12288
	v_add_u32_e32 v48, s19, v186
	s_cmp_eq_u64 vcc, exec
	s_waitcnt vmcnt(5)
	ds_write_b128 v48, v[64:67]
	v_max_f32_e32 v49, 0xf149f2ca, v72
	s_cselect_b64 vcc, -1, 0
	v_mov_b32_e32 v48, 0xf149f2ca
	v_cndmask_b32_e32 v210, v49, v48, vcc
	v_mul_f32_e32 v48, 0xbdd53b94, v210
	v_fmamk_f32 v0, v0, 0x3dd53b94, v48
	v_exp_f32_e32 v225, v0
	v_fmamk_f32 v0, v1, 0x3dd53b94, v48
	v_exp_f32_e32 v228, v0
	v_fmamk_f32 v0, v2, 0x3dd53b94, v48
	v_exp_f32_e32 v226, v0
	v_fmamk_f32 v0, v3, 0x3dd53b94, v48
	v_exp_f32_e32 v229, v0
	v_fmamk_f32 v0, v4, 0x3dd53b94, v48
	v_exp_f32_e32 v227, v0
	v_fmamk_f32 v0, v5, 0x3dd53b94, v48
	v_exp_f32_e32 v230, v0
	v_fmamk_f32 v0, v6, 0x3dd53b94, v48
	v_exp_f32_e32 v223, v0
	v_fmamk_f32 v0, v7, 0x3dd53b94, v48
	v_exp_f32_e32 v224, v0
	v_fmamk_f32 v0, v8, 0x3dd53b94, v48
	v_exp_f32_e32 v219, v0
	v_fmamk_f32 v0, v9, 0x3dd53b94, v48
	v_exp_f32_e32 v221, v0
	v_fmamk_f32 v0, v10, 0x3dd53b94, v48
	s_add_u32 s19, s28, s34
	v_pk_fma_f32 v[156:157], v[22:23], s[16:17], v[48:49] op_sel_hi:[1,0,0]
	v_sub_f32_e32 v22, 0xf149f2ca, v49
	v_exp_f32_e32 v220, v0
	v_fmamk_f32 v0, v11, 0x3dd53b94, v48
	s_addc_u32 s28, s29, s35
	v_mul_f32_e32 v22, 0x3dd53b94, v22
	v_exp_f32_e32 v222, v0
	v_fmamk_f32 v0, v12, 0x3dd53b94, v48
	s_add_u32 s18, s19, s18
	v_exp_f32_e32 v22, v22
	v_exp_f32_e32 v215, v0
	v_fmamk_f32 v0, v13, 0x3dd53b94, v48
	s_addc_u32 s19, s28, 0
	v_pk_fma_f32 v[148:149], v[30:31], s[16:17], v[48:49] op_sel_hi:[1,0,0]
	v_pk_fma_f32 v[150:151], v[28:29], s[16:17], v[48:49] op_sel_hi:[1,0,0]
	v_pk_fma_f32 v[152:153], v[26:27], s[16:17], v[48:49] op_sel_hi:[1,0,0]
	v_pk_fma_f32 v[154:155], v[24:25], s[16:17], v[48:49] op_sel_hi:[1,0,0]
	v_pk_fma_f32 v[158:159], v[20:21], s[16:17], v[48:49] op_sel_hi:[1,0,0]
	v_pk_fma_f32 v[160:161], v[18:19], s[16:17], v[48:49] op_sel_hi:[1,0,0]
	v_pk_fma_f32 v[162:163], v[16:17], s[16:17], v[48:49] op_sel_hi:[1,0,0]
	v_exp_f32_e32 v217, v0
	v_fmamk_f32 v0, v14, 0x3dd53b94, v48
	v_fmac_f32_e32 v48, 0x3dd53b94, v15
	s_add_u32 s18, s30, s18
	v_exp_f32_e32 v216, v0
	v_exp_f32_e32 v218, v48
	s_addc_u32 s19, s31, s19
	s_waitcnt lgkmcnt(0)
	s_barrier
	v_lshl_add_u64 v[0:1], s[18:19], 0, v[68:69]
	s_mov_b64 s[18:19], 0x120100
	v_cndmask_b32_e64 v209, v22, 1.0, vcc
	v_lshl_add_u64 v[168:169], v[0:1], 0, s[18:19]
	v_mov_b64_e32 v[62:63], v[46:47]
	v_mov_b64_e32 v[16:17], v[32:33]
	v_mov_b64_e32 v[0:1], v[32:33]
	v_mov_b64_e32 v[60:61], v[44:45]
	v_mov_b64_e32 v[58:59], v[42:43]
	v_mov_b64_e32 v[56:57], v[40:41]
	v_mov_b64_e32 v[54:55], v[38:39]
	v_mov_b64_e32 v[52:53], v[36:37]
	v_mov_b64_e32 v[50:51], v[34:35]
	v_mov_b64_e32 v[48:49], v[32:33]
	v_mov_b64_e32 v[18:19], v[34:35]
	v_mov_b64_e32 v[20:21], v[36:37]
	v_mov_b64_e32 v[22:23], v[38:39]
	v_mov_b64_e32 v[24:25], v[40:41]
	v_mov_b64_e32 v[26:27], v[42:43]
	v_mov_b64_e32 v[28:29], v[44:45]
	v_mov_b64_e32 v[30:31], v[46:47]
	v_mov_b64_e32 v[2:3], v[34:35]
	v_mov_b64_e32 v[4:5], v[36:37]
	v_mov_b64_e32 v[6:7], v[38:39]
	v_mov_b64_e32 v[8:9], v[40:41]
	v_mov_b64_e32 v[10:11], v[42:43]
	v_mov_b64_e32 v[12:13], v[44:45]
	v_mov_b64_e32 v[14:15], v[46:47]
	v_add_u32_e32 v199, 0x9000, v199
	v_add_u32_e32 v205, 0x9000, v205
	v_add_u32_e32 v206, 0x9000, v206
	v_add_u32_e32 v208, 0x9000, v208
	v_add_u32_e32 v207, 0x9000, v207
	v_add_u32_e32 v204, 0x9000, v204
	v_add_u32_e32 v203, 0x9000, v203
	v_add_u32_e32 v200, 0x9000, v200
	v_add_u32_e32 v191, 0x9000, v191
	v_add_u32_e32 v198, 0x9000, v198
	v_add_u32_e32 v187, 0x9000, v187
	v_add_u32_e32 v188, 0x9000, v188
	v_add_u32_e32 v202, 0x9000, v202
	v_add_u32_e32 v201, 0x9000, v201
	v_add_u32_e32 v189, 0x9000, v189
	v_add_u32_e32 v190, 0x9000, v190
	v_add_u32_e32 v185, 0x9000, v185
	v_add_u32_e32 v186, 0x9000, v186
; __device__ __forceinline__ void finishSM(f32x16& p0, f32x16& p1, float alpha, float& l_reg, bf16x8& pa0, bf16x8& pa1, bf16x8& pa2, bf16x8& pa3) {
; #pragma unroll
;   for (int r = 0; r < 16; ++r) p1[r] = __builtin_amdgcn_exp2f(p1[r]);
;   float ps = 0;
; #pragma unroll
;   for (int r = 0; r < 16; ++r) ps += p0[r];
; #pragma unroll
;   for (int r = 0; r < 16; ++r) ps += p1[r];
;   { auto rr = __builtin_amdgcn_permlane32_swap(__float_as_uint(ps), __float_as_uint(ps), false, false);
;     ps = __uint_as_float(rr[0]) + __uint_as_float(rr[1]); }
;   l_reg = l_reg * alpha + ps;
;     ...
;   PK4(p0, 0, pa0); PK4(p0, 8, pa1); PK4(p1, 0, pa2); PK4(p1, 8, pa3);
;     ...
; }
; __device__ __forceinline__ void qkt(f32x16& p0, f32x16& p1, const char* Ks, const bf16x8* qr, const char* qrl, int r32, int hi) {
;   p0 = f32x16{}; p1 = f32x16{};
; #pragma unroll
;   for (int d0 = 0; d0 < 8; ++d0) { int cb = (d0 * 16 + hi * 8) * 2;
;     bf16x8 b0 = *reinterpret_cast<const bf16x8*>(Ks + KSWZ(r32, cb));
;     bf16x8 b1 = *reinterpret_cast<const bf16x8*>(Ks + KSWZ(32 + r32, cb));
;     p0 = __builtin_amdgcn_mfma_f32_32x32x16_bf16(b0, qr[d0], p0, 0, 0, 0);
;     p1 = __builtin_amdgcn_mfma_f32_32x32x16_bf16(b1, qr[d0], p1, 0, 0, 0); }
; #pragma unroll
;   for (int d0 = 8; d0 < 12; ++d0) { int cb = (d0 * 16 + hi * 8) * 2;
;     bf16x8 b0 = *reinterpret_cast<const bf16x8*>(Ks + KSWZ(r32, cb));
;     bf16x8 b1 = *reinterpret_cast<const bf16x8*>(Ks + KSWZ(32 + r32, cb));
;     bf16x8 qf = *reinterpret_cast<const bf16x8*>(qrl + (((2 * (d0 - 8) + hi) ^ ((r32 >> 1) & 7)) << 4));
;     p0 = __builtin_amdgcn_mfma_f32_32x32x16_bf16(b0, qf, p0, 0, 0, 0);
;     p1 = __builtin_amdgcn_mfma_f32_32x32x16_bf16(b1, qf, p1, 0, 0, 0); }
; }
.LBB0_1151:
	s_sub_i32 s30, s76, 1
	s_cmp_eq_u32 s76, 0
	s_cselect_b32 s30, 2, s30
	s_add_i32 s18, s76, 1
	s_cmp_lg_u32 s76, 2
	s_cselect_b32 s18, s18, 0
	ds_read_b128 v[64:67], v199 offset:36864
	ds_read_b128 v[68:71], v199 offset:49152
	ds_read_b128 v[232:235], v205 offset:36864
	ds_read_b128 v[236:239], v205 offset:49152
	ds_read_b128 v[240:243], v206 offset:36864
	ds_read_b128 v[248:251], v206 offset:49152
	v_exp_f32_e32 v162, v162
	v_add_f32_e32 v211, v225, v228
	v_exp_f32_e32 v163, v163
	v_add_f32_e32 v211, v226, v211
	v_exp_f32_e32 v160, v160
	s_waitcnt lgkmcnt(4)
	v_mfma_f32_32x32x16_bf16 v[80:95], v[64:67], v[124:127], 0
	v_add_f32_e32 v211, v229, v211
	v_exp_f32_e32 v161, v161
	v_add_f32_e32 v211, v227, v211
	v_mfma_f32_32x32x16_bf16 v[64:79], v[68:71], v[124:127], 0
	v_exp_f32_e32 v158, v158
	v_add_f32_e32 v211, v230, v211
	s_waitcnt lgkmcnt(2)
	v_mfma_f32_32x32x16_bf16 v[80:95], v[232:235], v[120:123], v[80:95]
	ds_read_b128 v[232:235], v208 offset:36864
	v_exp_f32_e32 v159, v159
	v_add_f32_e32 v211, v223, v211
	v_mfma_f32_32x32x16_bf16 v[64:79], v[236:239], v[120:123], v[64:79]
	ds_read_b128 v[236:239], v208 offset:49152
	v_exp_f32_e32 v156, v156
	v_add_f32_e32 v211, v224, v211
	s_waitcnt lgkmcnt(2)
	v_mfma_f32_32x32x16_bf16 v[80:95], v[240:243], v[116:119], v[80:95]
	ds_read_b128 v[240:243], v207 offset:36864
	v_exp_f32_e32 v157, v157
	v_add_f32_e32 v211, v219, v211
	v_mfma_f32_32x32x16_bf16 v[64:79], v[248:251], v[116:119], v[64:79]
	ds_read_b128 v[248:251], v207 offset:49152
	v_exp_f32_e32 v154, v154
	v_add_f32_e32 v211, v221, v211
	s_waitcnt lgkmcnt(2)
	v_mfma_f32_32x32x16_bf16 v[80:95], v[232:235], v[112:115], v[80:95]
	ds_read_b128 v[232:235], v204 offset:36864
	v_exp_f32_e32 v155, v155
	v_add_f32_e32 v211, v220, v211
	v_mfma_f32_32x32x16_bf16 v[64:79], v[236:239], v[112:115], v[64:79]
	ds_read_b128 v[236:239], v204 offset:49152
	v_exp_f32_e32 v152, v152
	v_add_f32_e32 v211, v222, v211
	s_waitcnt lgkmcnt(2)
	v_mfma_f32_32x32x16_bf16 v[80:95], v[240:243], v[108:111], v[80:95]
	ds_read_b128 v[240:243], v203 offset:36864
	v_exp_f32_e32 v153, v153
	v_add_f32_e32 v211, v215, v211
	v_mfma_f32_32x32x16_bf16 v[64:79], v[248:251], v[108:111], v[64:79]
	ds_read_b128 v[248:251], v203 offset:49152
	v_exp_f32_e32 v150, v150
	v_add_f32_e32 v211, v217, v211
	s_waitcnt lgkmcnt(2)
	v_mfma_f32_32x32x16_bf16 v[80:95], v[232:235], v[104:107], v[80:95]
	ds_read_b128 v[232:235], v200 offset:36864
	v_exp_f32_e32 v151, v151
	v_add_f32_e32 v211, v216, v211
	v_mfma_f32_32x32x16_bf16 v[64:79], v[236:239], v[104:107], v[64:79]
	ds_read_b128 v[236:239], v200 offset:49152
	v_exp_f32_e32 v148, v148
	v_add_f32_e32 v211, v218, v211
	s_waitcnt lgkmcnt(2)
	v_mfma_f32_32x32x16_bf16 v[80:95], v[240:243], v[100:103], v[80:95]
	ds_read_b128 v[240:243], v191 offset:36864
	v_exp_f32_e32 v149, v149
	v_add_f32_e32 v212, v162, v163
	v_add_f32_e32 v212, v160, v212
	v_mfma_f32_32x32x16_bf16 v[64:79], v[248:251], v[100:103], v[64:79]
	ds_read_b128 v[248:251], v202 offset:49152
	v_add_f32_e32 v212, v161, v212
	v_add_f32_e32 v212, v158, v212
	v_add_f32_e32 v212, v159, v212
	v_add_f32_e32 v212, v156, v212
	s_waitcnt lgkmcnt(2)
	v_mfma_f32_32x32x16_bf16 v[80:95], v[232:235], v[96:99], v[80:95]
	ds_read_b128 v[232:235], v182
	v_add_f32_e32 v212, v157, v212
	v_add_f32_e32 v212, v154, v212
	v_add_f32_e32 v212, v155, v212
	v_add_f32_e32 v212, v152, v212
	v_mfma_f32_32x32x16_bf16 v[64:79], v[236:239], v[96:99], v[64:79]
	ds_read_b128 v[236:239], v198 offset:36864
	v_add_f32_e32 v212, v153, v212
	v_add_f32_e32 v212, v150, v212
	v_add_f32_e32 v212, v151, v212
	v_add_f32_e32 v212, v148, v212
	s_waitcnt lgkmcnt(1)
	v_mfma_f32_32x32x16_bf16 v[80:95], v[240:243], v[232:235], v[80:95]
	ds_read_b128 v[240:243], v201 offset:49152
	v_add_f32_e32 v212, v149, v212
	v_add_f32_e32 v211, v211, v212
	v_mov_b32_e32 v212, v211
	v_cvt_pk_bf16_f32 v158, v158, v159
	v_mfma_f32_32x32x16_bf16 v[64:79], v[248:251], v[232:235], v[64:79]
	ds_read_b128 v[248:251], v181
	ds_read_b128 v[232:235], v187 offset:36864
	v_cvt_pk_bf16_f32 v159, v156, v157
	v_permlane32_swap_b32_e32 v211, v212
	v_cvt_pk_bf16_f32 v156, v162, v163
	v_cvt_pk_bf16_f32 v157, v160, v161
	s_waitcnt lgkmcnt(1)
	v_mfma_f32_32x32x16_bf16 v[80:95], v[236:239], v[248:251], v[80:95]
	ds_read_b128 v[236:239], v189 offset:49152
	v_cvt_pk_bf16_f32 v160, v154, v155
	v_cvt_pk_bf16_f32 v161, v152, v153
	v_cvt_pk_bf16_f32 v162, v150, v151
	v_cvt_pk_bf16_f32 v163, v148, v149
	v_mfma_f32_32x32x16_bf16 v[64:79], v[240:243], v[248:251], v[64:79]
	ds_read_b128 v[240:243], v179
	ds_read_b128 v[248:251], v188 offset:36864
	v_add_f32_e32 v211, v211, v212
	v_cvt_pk_bf16_f32 v148, v225, v228
	v_cvt_pk_bf16_f32 v149, v226, v229
	v_cvt_pk_bf16_f32 v150, v227, v230
	s_waitcnt lgkmcnt(1)
	v_mfma_f32_32x32x16_bf16 v[80:95], v[232:235], v[240:243], v[80:95]
	ds_read_b128 v[232:235], v190 offset:49152
	v_cvt_pk_bf16_f32 v151, v223, v224
	v_cvt_pk_bf16_f32 v152, v219, v221
	v_cvt_pk_bf16_f32 v153, v220, v222
	v_cvt_pk_bf16_f32 v154, v215, v217
	v_mfma_f32_32x32x16_bf16 v[64:79], v[236:239], v[240:243], v[64:79]
	ds_read_b128 v[236:239], v177
	v_cvt_pk_bf16_f32 v155, v216, v218
	v_fma_f32 v176, v209, v176, v211
	s_waitcnt lgkmcnt(0)
	v_mfma_f32_32x32x16_bf16 v[80:95], v[248:251], v[236:239], v[80:95]
	v_mfma_f32_32x32x16_bf16 v[64:79], v[232:235], v[236:239], v[64:79]
	s_lshl_b32 s31, s30, 14
	v_add_u32_e32 v180, s31, v178
	ds_read_b64_tr_b16 v[240:241], v180 offset:0
	ds_read_b64_tr_b16 v[242:243], v180 offset:2048
	ds_read_b64_tr_b16 v[248:249], v180 offset:512
	ds_read_b64_tr_b16 v[250:251], v180 offset:2560
	ds_read_b64_tr_b16 v[232:233], v180 offset:1024
	ds_read_b64_tr_b16 v[234:235], v180 offset:3072
	ds_read_b64_tr_b16 v[236:237], v180 offset:1536
	ds_read_b64_tr_b16 v[238:239], v180 offset:3584
	s_lshl_b32 s19, s18, 14
	v_add_u32_e32 v231, s19, v183
	s_waitcnt vmcnt(0)
; #define SBAR() __builtin_amdgcn_sched_barrier(0)
; __device__ __forceinline__ void partialSM(f32x16& p0, f32x16& p1, float& m_reg, float& mn, float& alpha) {
;   constexpr float C = SCALE * 1.4426950408889634f;
;   float pmax = p0[0];
; #pragma unroll
;   for (int r = 1; r < 16; ++r) pmax = fmaxf(pmax, p0[r]);
; #pragma unroll
;   for (int r = 0; r < 16; ++r) pmax = fmaxf(pmax, p1[r]);
;   { auto rr = __builtin_amdgcn_permlane32_swap(__float_as_uint(pmax), __float_as_uint(pmax), false, false);
;     pmax = fmaxf(__uint_as_float(rr[0]), __uint_as_float(rr[1])); }
;   if (__builtin_expect(__all(pmax - m_reg <= THR / SCALE), 1)) { mn = m_reg; alpha = 1.f; }
;   else { mn = fmaxf(m_reg, pmax); alpha = __builtin_amdgcn_exp2f((m_reg - mn) * C); m_reg = mn; }
;   float mnC = -mn * C;
; #pragma unroll
;   for (int r = 0; r < 16; ++r) p0[r] = fmaf(p0[r], C, mnC);
; #pragma unroll
;   for (int r = 0; r < 16; ++r) p1[r] = fmaf(p1[r], C, mnC);
; #pragma unroll
;   for (int r = 0; r < 16; ++r) p0[r] = __builtin_amdgcn_exp2f(p0[r]);
; }
; template <int D0> __device__ __forceinline__ void pv_one(f32x16& od, int vb, bf16x8 pa0, bf16x8 pa1, bf16x8 pa2, bf16x8 pa3) {
;   const s16x4 l0 = tr_read<v_rd_off(D0, 0, 0)>(vb), h0 = tr_read<v_rd_off(D0, 0, 1)>(vb), l1 = tr_read<v_rd_off(D0, 1, 0)>(vb), h1 = tr_read<v_rd_off(D0, 1, 1)>(vb);
;   const s16x4 l2 = tr_read<v_rd_off(D0, 2, 0)>(vb), h2 = tr_read<v_rd_off(D0, 2, 1)>(vb), l3 = tr_read<v_rd_off(D0, 3, 0)>(vb), h3 = tr_read<v_rd_off(D0, 3, 1)>(vb);
;   asm volatile("s_waitcnt lgkmcnt(0)" ::: "memory"); SBAR();
;     ...
;   od = __builtin_amdgcn_mfma_f32_32x32x16_bf16(pa0, PK(l0, h0), od, 0, 0, 0);
;   od = __builtin_amdgcn_mfma_f32_32x32x16_bf16(pa1, PK(l1, h1), od, 0, 0, 0);
;   od = __builtin_amdgcn_mfma_f32_32x32x16_bf16(pa2, PK(l2, h2), od, 0, 0, 0);
;   od = __builtin_amdgcn_mfma_f32_32x32x16_bf16(pa3, PK(l3, h3), od, 0, 0, 0);
;     ...
; }
; __device__ __forceinline__ void pv_d0(f32x16* o, int vb, bf16x8 pa0, bf16x8 pa1, bf16x8 pa2, bf16x8 pa3) {
;   pv_one<0>(o[0], vb, pa0, pa1, pa2, pa3); pv_one<1>(o[1], vb, pa0, pa1, pa2, pa3); pv_one<2>(o[2], vb, pa0, pa1, pa2, pa3); pv_one<3>(o[3], vb, pa0, pa1, pa2, pa3);
	ds_write_b128 v231, v[140:143]
	v_add_u32_e32 v140, s19, v184
	ds_write_b128 v140, v[144:147]
	ds_write_b128 v185, v[136:139] offset:12288
	ds_write_b128 v185, v[132:135] offset:24576
	s_mov_b32 s18, 0xfffa0000
	ds_write_b128 v186, v[128:131] offset:12288
	v_add_co_u32_e32 v128, vcc, s18, v168
	s_mov_b32 s18, 0xfffc0000
	s_nop 0
	v_addc_co_u32_e32 v129, vcc, -1, v169, vcc
	v_add_co_u32_e32 v130, vcc, s18, v168
	s_movk_i32 s18, 0xe000
	s_nop 0
	v_addc_co_u32_e32 v131, vcc, -1, v169, vcc
	global_load_dwordx4 v[140:143], v[128:129], off
	global_load_dwordx4 v[136:139], v[128:129], off offset:-256
	global_load_dwordx4 v[144:147], v[130:131], off
	global_load_dwordx4 v[132:135], v[130:131], off offset:-256
	v_add_co_u32_e32 v128, vcc, s18, v166
	s_nop 1
	v_addc_co_u32_e32 v129, vcc, -1, v167, vcc
	global_load_dwordx4 v[128:131], v[128:129], off
	v_max3_f32 v194, v80, v81, v82
	v_max3_f32 v195, v64, v65, v66
	v_max3_f32 v194, v194, v83, v84
	v_max3_f32 v195, v195, v67, v68
	v_max3_f32 v194, v194, v85, v86
	v_max3_f32 v195, v195, v69, v70
	s_waitcnt lgkmcnt(9)
	v_mfma_f32_32x32x16_bf16 v[32:47], v[148:151], v[240:243], v[32:47]
	ds_read_b64_tr_b16 v[240:241], v180 offset:4096
	ds_read_b64_tr_b16 v[242:243], v180 offset:6144
	v_max3_f32 v194, v194, v87, v88
	v_max3_f32 v195, v195, v71, v72
	v_max3_f32 v194, v194, v89, v90
	v_max3_f32 v195, v195, v73, v74
	v_max3_f32 v194, v194, v91, v92
	v_max3_f32 v195, v195, v75, v76
	v_mfma_f32_32x32x16_bf16 v[48:63], v[148:151], v[248:251], v[48:63]
	ds_read_b64_tr_b16 v[248:249], v180 offset:4608
	ds_read_b64_tr_b16 v[250:251], v180 offset:6656
	v_max3_f32 v194, v194, v93, v94
	v_max3_f32 v195, v195, v77, v78
	v_max3_f32 v194, v194, v95, v195
	v_max_f32_e32 v194, v194, v79
	v_mov_b32_e32 v195, v194
	s_nop 1
	s_waitcnt lgkmcnt(9)
	v_mfma_f32_32x32x16_bf16 v[16:31], v[148:151], v[232:235], v[16:31]
	ds_read_b64_tr_b16 v[232:233], v180 offset:5120
	ds_read_b64_tr_b16 v[234:235], v180 offset:7168
	v_permlane32_swap_b32_e32 v194, v195
	v_max_f32_e32 v194, v194, v195
	v_sub_f32_e32 v195, v194, v210
	v_cmp_ge_f32_e32 vcc, s15, v195
	v_mfma_f32_32x32x16_bf16 v[0:15], v[148:151], v[236:239], v[0:15]
	ds_read_b64_tr_b16 v[236:237], v180 offset:5632
	ds_read_b64_tr_b16 v[238:239], v180 offset:7680
	s_cmp_eq_u64 vcc, exec
	s_cselect_b64 s[40:41], -1, 0
	s_cbranch_scc1 .Lattn_fast1
	v_max_f32_e32 v194, v210, v194
	v_sub_f32_e32 v195, v210, v194
	v_mul_f32_e32 v195, 0x3dd53b94, v195
	v_exp_f32_e32 v214, v195
	v_mov_b32_e32 v210, v194
	s_branch .Lattn_join1
.Lattn_fast1:
	v_mov_b32_e32 v214, 1.0
.Lattn_join1:
	v_mul_f32_e32 v194, 0xbdd53b94, v210
	v_fmamk_f32 v80, v80, 0x3dd53b94, v194
	v_fmamk_f32 v81, v81, 0x3dd53b94, v194
	s_waitcnt lgkmcnt(4)
	v_mfma_f32_32x32x16_bf16 v[32:47], v[152:155], v[240:243], v[32:47]
	ds_read_b64_tr_b16 v[240:241], v180 offset:8192
	ds_read_b64_tr_b16 v[242:243], v180 offset:10240
	v_fmamk_f32 v82, v82, 0x3dd53b94, v194
	v_exp_f32_e32 v225, v80
	v_fmamk_f32 v83, v83, 0x3dd53b94, v194
	v_exp_f32_e32 v228, v81
	v_mfma_f32_32x32x16_bf16 v[48:63], v[152:155], v[248:251], v[48:63]
	ds_read_b64_tr_b16 v[248:249], v180 offset:8704
	ds_read_b64_tr_b16 v[250:251], v180 offset:10752
	v_fmamk_f32 v150, v76, 0x3dd53b94, v194
	v_fmamk_f32 v151, v77, 0x3dd53b94, v194
	v_fmamk_f32 v148, v78, 0x3dd53b94, v194
	v_fmamk_f32 v149, v79, 0x3dd53b94, v194
	v_fmamk_f32 v84, v84, 0x3dd53b94, v194
	s_waitcnt lgkmcnt(4)
	v_mfma_f32_32x32x16_bf16 v[16:31], v[152:155], v[232:235], v[16:31]
	ds_read_b64_tr_b16 v[232:233], v180 offset:9216
	ds_read_b64_tr_b16 v[234:235], v180 offset:11264
	v_exp_f32_e32 v226, v82
	v_fmamk_f32 v85, v85, 0x3dd53b94, v194
	v_exp_f32_e32 v229, v83
	v_fmamk_f32 v86, v86, 0x3dd53b94, v194
	v_mfma_f32_32x32x16_bf16 v[0:15], v[152:155], v[236:239], v[0:15]
	ds_read_b64_tr_b16 v[236:237], v180 offset:9728
	ds_read_b64_tr_b16 v[238:239], v180 offset:11776
	v_exp_f32_e32 v227, v84
	v_fmamk_f32 v87, v87, 0x3dd53b94, v194
	v_exp_f32_e32 v230, v85
	v_fmamk_f32 v154, v72, 0x3dd53b94, v194
	s_waitcnt lgkmcnt(4)
	v_mfma_f32_32x32x16_bf16 v[32:47], v[156:159], v[240:243], v[32:47]
	ds_read_b64_tr_b16 v[240:241], v180 offset:12288
	ds_read_b64_tr_b16 v[242:243], v180 offset:14336
	v_fmamk_f32 v155, v73, 0x3dd53b94, v194
	v_fmamk_f32 v152, v74, 0x3dd53b94, v194
	v_fmamk_f32 v153, v75, 0x3dd53b94, v194
	v_fmamk_f32 v88, v88, 0x3dd53b94, v194
	v_exp_f32_e32 v223, v86
	v_mfma_f32_32x32x16_bf16 v[48:63], v[156:159], v[248:251], v[48:63]
	ds_read_b64_tr_b16 v[248:249], v180 offset:12800
	ds_read_b64_tr_b16 v[250:251], v180 offset:14848
	v_fmamk_f32 v89, v89, 0x3dd53b94, v194
	v_exp_f32_e32 v224, v87
	v_fmamk_f32 v90, v90, 0x3dd53b94, v194
	v_exp_f32_e32 v219, v88
	s_waitcnt lgkmcnt(4)
	v_mfma_f32_32x32x16_bf16 v[16:31], v[156:159], v[232:235], v[16:31]
	ds_read_b64_tr_b16 v[232:233], v180 offset:13312
	ds_read_b64_tr_b16 v[234:235], v180 offset:15360
	v_fmamk_f32 v91, v91, 0x3dd53b94, v194
	v_exp_f32_e32 v221, v89
	v_fmamk_f32 v92, v92, 0x3dd53b94, v194
	v_exp_f32_e32 v220, v90
	v_mfma_f32_32x32x16_bf16 v[0:15], v[156:159], v[236:239], v[0:15]
	ds_read_b64_tr_b16 v[236:237], v180 offset:13824
	ds_read_b64_tr_b16 v[238:239], v180 offset:15872
	v_fmamk_f32 v158, v68, 0x3dd53b94, v194
	v_fmamk_f32 v159, v69, 0x3dd53b94, v194
	v_fmamk_f32 v156, v70, 0x3dd53b94, v194
	v_fmamk_f32 v157, v71, 0x3dd53b94, v194
	v_fmamk_f32 v93, v93, 0x3dd53b94, v194
	s_waitcnt lgkmcnt(4)
	v_mfma_f32_32x32x16_bf16 v[32:47], v[160:163], v[240:243], v[32:47]
	v_exp_f32_e32 v222, v91
	v_fmamk_f32 v94, v94, 0x3dd53b94, v194
	v_exp_f32_e32 v215, v92
	v_fmamk_f32 v95, v95, 0x3dd53b94, v194
	v_mfma_f32_32x32x16_bf16 v[48:63], v[160:163], v[248:251], v[48:63]
	v_exp_f32_e32 v217, v93
	v_exp_f32_e32 v216, v94
	v_exp_f32_e32 v218, v95
	s_waitcnt lgkmcnt(0)
	v_mfma_f32_32x32x16_bf16 v[16:31], v[160:163], v[232:235], v[16:31]
	v_mfma_f32_32x32x16_bf16 v[0:15], v[160:163], v[236:239], v[0:15]
	v_fmamk_f32 v162, v64, 0x3dd53b94, v194
	v_fmamk_f32 v163, v65, 0x3dd53b94, v194
	v_fmamk_f32 v160, v66, 0x3dd53b94, v194
	v_fmamk_f32 v161, v67, 0x3dd53b94, v194
	s_and_b64 vcc, exec, s[40:41]
	s_cbranch_vccnz .Lattn_skip_rs1
; __device__ __forceinline__ void finishSM(f32x16& p0, f32x16& p1, float alpha, float& l_reg, bf16x8& pa0, bf16x8& pa1, bf16x8& pa2, bf16x8& pa3) {
; #pragma unroll
;   for (int r = 0; r < 16; ++r) p1[r] = __builtin_amdgcn_exp2f(p1[r]);
;   float ps = 0;
; #pragma unroll
;   for (int r = 0; r < 16; ++r) ps += p0[r];
; #pragma unroll
;   for (int r = 0; r < 16; ++r) ps += p1[r];
;   { auto rr = __builtin_amdgcn_permlane32_swap(__float_as_uint(ps), __float_as_uint(ps), false, false);
;     ps = __uint_as_float(rr[0]) + __uint_as_float(rr[1]); }
;   l_reg = l_reg * alpha + ps;
;     ...
;   PK4(p0, 0, pa0); PK4(p0, 8, pa1); PK4(p1, 0, pa2); PK4(p1, 8, pa3);
;     ...
; }
; __device__ __forceinline__ void qkt(f32x16& p0, f32x16& p1, const char* Ks, const bf16x8* qr, const char* qrl, int r32, int hi) {
;   p0 = f32x16{}; p1 = f32x16{};
; #pragma unroll
;   for (int d0 = 0; d0 < 8; ++d0) { int cb = (d0 * 16 + hi * 8) * 2;
;     bf16x8 b0 = *reinterpret_cast<const bf16x8*>(Ks + KSWZ(r32, cb));
;     bf16x8 b1 = *reinterpret_cast<const bf16x8*>(Ks + KSWZ(32 + r32, cb));
;     p0 = __builtin_amdgcn_mfma_f32_32x32x16_bf16(b0, qr[d0], p0, 0, 0, 0);
;     p1 = __builtin_amdgcn_mfma_f32_32x32x16_bf16(b1, qr[d0], p1, 0, 0, 0); }
; #pragma unroll
;   for (int d0 = 8; d0 < 12; ++d0) { int cb = (d0 * 16 + hi * 8) * 2;
;     bf16x8 b0 = *reinterpret_cast<const bf16x8*>(Ks + KSWZ(r32, cb));
;     bf16x8 b1 = *reinterpret_cast<const bf16x8*>(Ks + KSWZ(32 + r32, cb));
;     bf16x8 qf = *reinterpret_cast<const bf16x8*>(qrl + (((2 * (d0 - 8) + hi) ^ ((r32 >> 1) & 7)) << 4));
;     p0 = __builtin_amdgcn_mfma_f32_32x32x16_bf16(b0, qf, p0, 0, 0, 0);
;     p1 = __builtin_amdgcn_mfma_f32_32x32x16_bf16(b1, qf, p1, 0, 0, 0); }
; }
; __device__ __forceinline__ void attn_unit(const bf16_t* __restrict__ Qb, const bf16_t* __restrict__ Kn, const bf16_t* __restrict__ Vh, const bf16_t* __restrict__ Kr,
;                                           bf16_t* GO, int seq, char* lds, const int tid) {
;     ...
;   f32x16 pA0, pA1, pB0, pB1; float mnA, mnB, alA, alB; bf16x8 pa0, pa1, pa2, pa3; const int NT = seq / KVBLK;
	s_and_saveexec_b64 s[18:19], s[38:39]
	ds_write_b32 v175, v214 offset:128
	s_or_b64 exec, exec, s[18:19]
	s_waitcnt lgkmcnt(0)
	v_add_u32_e32 v194, v173, v164
	ds_read_b128 v[232:235], v194 offset:224
	ds_read_b128 v[236:239], v194 offset:192
	ds_read_b128 v[240:243], v194 offset:160
	ds_read_b128 v[248:251], v194 offset:128
	s_waitcnt lgkmcnt(0)
	v_pk_mul_f32 v[44:45], v[44:45], v[232:233]
	v_pk_mul_f32 v[46:47], v[46:47], v[234:235]
	v_pk_mul_f32 v[40:41], v[40:41], v[236:237]
	v_pk_mul_f32 v[42:43], v[42:43], v[238:239]
	v_pk_mul_f32 v[36:37], v[36:37], v[240:241]
	v_pk_mul_f32 v[38:39], v[38:39], v[242:243]
	v_pk_mul_f32 v[32:33], v[32:33], v[248:249]
	v_pk_mul_f32 v[34:35], v[34:35], v[250:251]
	v_pk_mul_f32 v[60:61], v[60:61], v[232:233]
	v_pk_mul_f32 v[62:63], v[62:63], v[234:235]
	v_pk_mul_f32 v[56:57], v[56:57], v[236:237]
	v_pk_mul_f32 v[58:59], v[58:59], v[238:239]
	v_pk_mul_f32 v[52:53], v[52:53], v[240:241]
	v_pk_mul_f32 v[54:55], v[54:55], v[242:243]
	v_pk_mul_f32 v[48:49], v[48:49], v[248:249]
	v_pk_mul_f32 v[50:51], v[50:51], v[250:251]
	v_pk_mul_f32 v[28:29], v[28:29], v[232:233]
	v_pk_mul_f32 v[30:31], v[30:31], v[234:235]
	v_pk_mul_f32 v[24:25], v[24:25], v[236:237]
	v_pk_mul_f32 v[26:27], v[26:27], v[238:239]
	v_pk_mul_f32 v[20:21], v[20:21], v[240:241]
	v_pk_mul_f32 v[22:23], v[22:23], v[242:243]
	v_pk_mul_f32 v[16:17], v[16:17], v[248:249]
	v_pk_mul_f32 v[18:19], v[18:19], v[250:251]
	v_pk_mul_f32 v[12:13], v[12:13], v[232:233]
	v_pk_mul_f32 v[14:15], v[14:15], v[234:235]
	v_pk_mul_f32 v[8:9], v[8:9], v[236:237]
	v_pk_mul_f32 v[10:11], v[10:11], v[238:239]
	v_pk_mul_f32 v[4:5], v[4:5], v[240:241]
	v_pk_mul_f32 v[6:7], v[6:7], v[242:243]
	v_pk_mul_f32 v[0:1], v[0:1], v[248:249]
	v_pk_mul_f32 v[2:3], v[2:3], v[250:251]
.Lattn_skip_rs1:
	s_waitcnt lgkmcnt(0)
	s_barrier
	ds_read_b128 v[64:67], v199 offset:12288
	ds_read_b128 v[68:71], v199 offset:24576
	ds_read_b128 v[232:235], v205 offset:12288
	ds_read_b128 v[236:239], v205 offset:24576
	ds_read_b128 v[240:243], v206 offset:12288
	ds_read_b128 v[248:251], v206 offset:24576
	v_exp_f32_e32 v162, v162
	v_add_f32_e32 v211, v225, v228
	v_exp_f32_e32 v163, v163
	v_add_f32_e32 v211, v226, v211
	v_exp_f32_e32 v160, v160
	s_waitcnt lgkmcnt(4)
	v_mfma_f32_32x32x16_bf16 v[80:95], v[64:67], v[124:127], 0
	v_add_f32_e32 v211, v229, v211
	v_exp_f32_e32 v161, v161
	v_add_f32_e32 v211, v227, v211
	v_mfma_f32_32x32x16_bf16 v[64:79], v[68:71], v[124:127], 0
	v_exp_f32_e32 v158, v158
	v_add_f32_e32 v211, v230, v211
	s_waitcnt lgkmcnt(2)
	v_mfma_f32_32x32x16_bf16 v[80:95], v[232:235], v[120:123], v[80:95]
	ds_read_b128 v[232:235], v208 offset:12288
	v_exp_f32_e32 v159, v159
	v_add_f32_e32 v211, v223, v211
	v_mfma_f32_32x32x16_bf16 v[64:79], v[236:239], v[120:123], v[64:79]
	ds_read_b128 v[236:239], v208 offset:24576
	v_exp_f32_e32 v156, v156
	v_add_f32_e32 v211, v224, v211
	s_waitcnt lgkmcnt(2)
	v_mfma_f32_32x32x16_bf16 v[80:95], v[240:243], v[116:119], v[80:95]
	ds_read_b128 v[240:243], v207 offset:12288
	v_exp_f32_e32 v157, v157
	v_add_f32_e32 v211, v219, v211
	v_mfma_f32_32x32x16_bf16 v[64:79], v[248:251], v[116:119], v[64:79]
	ds_read_b128 v[248:251], v207 offset:24576
	v_exp_f32_e32 v154, v154
	v_add_f32_e32 v211, v221, v211
	s_waitcnt lgkmcnt(2)
	v_mfma_f32_32x32x16_bf16 v[80:95], v[232:235], v[112:115], v[80:95]
	ds_read_b128 v[232:235], v204 offset:12288
	v_exp_f32_e32 v155, v155
	v_add_f32_e32 v211, v220, v211
	v_mfma_f32_32x32x16_bf16 v[64:79], v[236:239], v[112:115], v[64:79]
	ds_read_b128 v[236:239], v204 offset:24576
	v_exp_f32_e32 v152, v152
	v_add_f32_e32 v211, v222, v211
	s_waitcnt lgkmcnt(2)
	v_mfma_f32_32x32x16_bf16 v[80:95], v[240:243], v[108:111], v[80:95]
	ds_read_b128 v[240:243], v203 offset:12288
	v_exp_f32_e32 v153, v153
	v_add_f32_e32 v211, v215, v211
	v_mfma_f32_32x32x16_bf16 v[64:79], v[248:251], v[108:111], v[64:79]
	ds_read_b128 v[248:251], v203 offset:24576
	v_exp_f32_e32 v150, v150
	v_add_f32_e32 v211, v217, v211
	s_waitcnt lgkmcnt(2)
	v_mfma_f32_32x32x16_bf16 v[80:95], v[232:235], v[104:107], v[80:95]
	ds_read_b128 v[232:235], v200 offset:12288
	v_exp_f32_e32 v151, v151
	v_add_f32_e32 v211, v216, v211
	v_mfma_f32_32x32x16_bf16 v[64:79], v[236:239], v[104:107], v[64:79]
	ds_read_b128 v[236:239], v200 offset:24576
	v_exp_f32_e32 v148, v148
	v_add_f32_e32 v211, v218, v211
	s_waitcnt lgkmcnt(2)
	v_mfma_f32_32x32x16_bf16 v[80:95], v[240:243], v[100:103], v[80:95]
	ds_read_b128 v[240:243], v191 offset:12288
	v_exp_f32_e32 v149, v149
	v_add_f32_e32 v212, v162, v163
	v_add_f32_e32 v212, v160, v212
	v_mfma_f32_32x32x16_bf16 v[64:79], v[248:251], v[100:103], v[64:79]
	ds_read_b128 v[248:251], v202 offset:24576
	v_add_f32_e32 v212, v161, v212
	v_add_f32_e32 v212, v158, v212
	v_add_f32_e32 v212, v159, v212
	v_add_f32_e32 v212, v156, v212
	s_waitcnt lgkmcnt(2)
	v_mfma_f32_32x32x16_bf16 v[80:95], v[232:235], v[96:99], v[80:95]
	ds_read_b128 v[232:235], v182
	v_add_f32_e32 v212, v157, v212
	v_add_f32_e32 v212, v154, v212
	v_add_f32_e32 v212, v155, v212
	v_add_f32_e32 v212, v152, v212
	v_mfma_f32_32x32x16_bf16 v[64:79], v[236:239], v[96:99], v[64:79]
	ds_read_b128 v[236:239], v198 offset:12288
	v_add_f32_e32 v212, v153, v212
	v_add_f32_e32 v212, v150, v212
	v_add_f32_e32 v212, v151, v212
	v_add_f32_e32 v212, v148, v212
	s_waitcnt lgkmcnt(1)
	v_mfma_f32_32x32x16_bf16 v[80:95], v[240:243], v[232:235], v[80:95]
	ds_read_b128 v[240:243], v201 offset:24576
	v_add_f32_e32 v212, v149, v212
	v_add_f32_e32 v211, v211, v212
	v_mov_b32_e32 v212, v211
	v_cvt_pk_bf16_f32 v158, v158, v159
	v_mfma_f32_32x32x16_bf16 v[64:79], v[248:251], v[232:235], v[64:79]
	ds_read_b128 v[248:251], v181
	ds_read_b128 v[232:235], v187 offset:12288
	v_cvt_pk_bf16_f32 v159, v156, v157
	v_permlane32_swap_b32_e32 v211, v212
	v_cvt_pk_bf16_f32 v156, v162, v163
	v_cvt_pk_bf16_f32 v157, v160, v161
	s_waitcnt lgkmcnt(1)
; #define SBAR() __builtin_amdgcn_sched_barrier(0)
; #define RESC(a) do { if (__any((a) < 1.f)) { if (hi == 0) al_l[r32] = (a); asm volatile("s_waitcnt lgkmcnt(0)" ::: "memory"); \
;     _Pragma("unroll") for (int d = 0; d < 4; ++d) _Pragma("unroll") for (int r = 0; r < 16; ++r) o[d][r] *= al_l[crow(r, hi)]; } } while (0)
; #define LBAR() do { asm volatile("s_waitcnt lgkmcnt(0)" ::: "memory"); __builtin_amdgcn_s_barrier(); asm volatile("" ::: "memory"); } while (0)
; __device__ __forceinline__ void finishSM(f32x16& p0, f32x16& p1, float alpha, float& l_reg, bf16x8& pa0, bf16x8& pa1, bf16x8& pa2, bf16x8& pa3) {
; #pragma unroll
;   for (int r = 0; r < 16; ++r) p1[r] = __builtin_amdgcn_exp2f(p1[r]);
;   float ps = 0;
; #pragma unroll
;   for (int r = 0; r < 16; ++r) ps += p0[r];
; #pragma unroll
;   for (int r = 0; r < 16; ++r) ps += p1[r];
;   { auto rr = __builtin_amdgcn_permlane32_swap(__float_as_uint(ps), __float_as_uint(ps), false, false);
;     ps = __uint_as_float(rr[0]) + __uint_as_float(rr[1]); }
;   l_reg = l_reg * alpha + ps;
;     ...
;   PK4(p0, 0, pa0); PK4(p0, 8, pa1); PK4(p1, 0, pa2); PK4(p1, 8, pa3);
;     ...
; }
; __device__ __forceinline__ void attn_unit(const bf16_t* __restrict__ Qb, const bf16_t* __restrict__ Kn, const bf16_t* __restrict__ Vh, const bf16_t* __restrict__ Kr,
;                                           bf16_t* GO, int seq, char* lds, const int tid) {
;     ...
;     SWRITE(bp, 0); if (j + 3 < NT) SLOAD(0, (j + 3) * KVBLK); SBAR();
;     pv_d0(o, vb0 + bc * SHM_V, pa0, pa1, pa2, pa3); partialSM(pA0, pA1, m_reg, mnA, alA);
;     RESC(alA); LBAR();
	v_mfma_f32_32x32x16_bf16 v[80:95], v[236:239], v[248:251], v[80:95]
	ds_read_b128 v[236:239], v189 offset:24576
	v_cvt_pk_bf16_f32 v160, v154, v155
	v_cvt_pk_bf16_f32 v161, v152, v153
	v_cvt_pk_bf16_f32 v162, v150, v151
	v_cvt_pk_bf16_f32 v163, v148, v149
	v_mfma_f32_32x32x16_bf16 v[64:79], v[240:243], v[248:251], v[64:79]
	ds_read_b128 v[240:243], v179
	ds_read_b128 v[248:251], v188 offset:12288
	v_add_f32_e32 v211, v211, v212
	v_cvt_pk_bf16_f32 v148, v225, v228
	v_cvt_pk_bf16_f32 v149, v226, v229
	v_cvt_pk_bf16_f32 v150, v227, v230
	s_waitcnt lgkmcnt(1)
	v_mfma_f32_32x32x16_bf16 v[80:95], v[232:235], v[240:243], v[80:95]
	ds_read_b128 v[232:235], v190 offset:24576
	v_cvt_pk_bf16_f32 v151, v223, v224
	v_cvt_pk_bf16_f32 v152, v219, v221
	v_cvt_pk_bf16_f32 v153, v220, v222
	v_cvt_pk_bf16_f32 v154, v215, v217
	v_mfma_f32_32x32x16_bf16 v[64:79], v[236:239], v[240:243], v[64:79]
	ds_read_b128 v[236:239], v177
	v_cvt_pk_bf16_f32 v155, v216, v218
	v_fma_f32 v176, v214, v176, v211
	s_waitcnt lgkmcnt(0)
	v_mfma_f32_32x32x16_bf16 v[80:95], v[248:251], v[236:239], v[80:95]
	v_mfma_f32_32x32x16_bf16 v[64:79], v[232:235], v[236:239], v[64:79]
	v_lshl_add_u32 v231, s76, 14, v178
	ds_read_b64_tr_b16 v[240:241], v231 offset:0
	ds_read_b64_tr_b16 v[242:243], v231 offset:2048
	ds_read_b64_tr_b16 v[248:249], v231 offset:512
	ds_read_b64_tr_b16 v[250:251], v231 offset:2560
	ds_read_b64_tr_b16 v[232:233], v231 offset:1024
	ds_read_b64_tr_b16 v[234:235], v231 offset:3072
	ds_read_b64_tr_b16 v[236:237], v231 offset:1536
	ds_read_b64_tr_b16 v[238:239], v231 offset:3584
	v_add_u32_e32 v194, s31, v183
	s_waitcnt vmcnt(4)
	ds_write_b128 v194, v[140:143]
	v_add_u32_e32 v194, s31, v184
	s_add_i32 s73, s73, 2
	s_cmp_ge_u32 s73, s45
	s_waitcnt vmcnt(2)
	ds_write_b128 v194, v[144:147]
	s_cselect_b64 s[28:29], -1, 0
	ds_write_b128 v185, v[136:139] offset:36864
	s_waitcnt vmcnt(1)
	ds_write_b128 v185, v[132:135] offset:49152
	s_and_b64 vcc, exec, s[28:29]
	s_waitcnt vmcnt(0)
	ds_write_b128 v186, v[128:131] offset:36864
	s_cbranch_vccnz .LBB0_1157
	v_add_co_u32_e32 v128, vcc, 0xfffe0000, v168
	s_nop 1
	v_addc_co_u32_e32 v129, vcc, -1, v169, vcc
	global_load_dwordx4 v[140:143], v[128:129], off
	global_load_dwordx4 v[136:139], v[128:129], off offset:-256
	global_load_dwordx4 v[144:147], v[168:169], off
	global_load_dwordx4 v[132:135], v[168:169], off offset:-256
	s_nop 0
	global_load_dwordx4 v[128:131], v[166:167], off
.LBB0_1157:
	v_max3_f32 v194, v80, v81, v82
	v_max3_f32 v195, v64, v65, v66
	v_max3_f32 v194, v194, v83, v84
	v_max3_f32 v195, v195, v67, v68
	v_max3_f32 v194, v194, v85, v86
	v_max3_f32 v195, v195, v69, v70
	s_waitcnt lgkmcnt(9)
	v_mfma_f32_32x32x16_bf16 v[32:47], v[148:151], v[240:243], v[32:47]
	ds_read_b64_tr_b16 v[240:241], v231 offset:4096
	ds_read_b64_tr_b16 v[242:243], v231 offset:6144
	v_max3_f32 v194, v194, v87, v88
	v_max3_f32 v195, v195, v71, v72
	v_max3_f32 v194, v194, v89, v90
	v_max3_f32 v195, v195, v73, v74
	v_max3_f32 v194, v194, v91, v92
	v_max3_f32 v195, v195, v75, v76
	v_mfma_f32_32x32x16_bf16 v[48:63], v[148:151], v[248:251], v[48:63]
	ds_read_b64_tr_b16 v[248:249], v231 offset:4608
	ds_read_b64_tr_b16 v[250:251], v231 offset:6656
	v_max3_f32 v194, v194, v93, v94
	v_max3_f32 v195, v195, v77, v78
	v_max3_f32 v194, v194, v95, v195
	v_max_f32_e32 v194, v194, v79
	v_mov_b32_e32 v195, v194
	s_nop 1
	s_waitcnt lgkmcnt(9)
	v_mfma_f32_32x32x16_bf16 v[16:31], v[148:151], v[232:235], v[16:31]
	ds_read_b64_tr_b16 v[232:233], v231 offset:5120
	ds_read_b64_tr_b16 v[234:235], v231 offset:7168
	v_permlane32_swap_b32_e32 v194, v195
	v_max_f32_e32 v194, v194, v195
	v_sub_f32_e32 v195, v194, v210
	v_cmp_ge_f32_e32 vcc, s15, v195
	v_mfma_f32_32x32x16_bf16 v[0:15], v[148:151], v[236:239], v[0:15]
	ds_read_b64_tr_b16 v[236:237], v231 offset:5632
	ds_read_b64_tr_b16 v[238:239], v231 offset:7680
	s_cmp_eq_u64 vcc, exec
	s_cselect_b64 s[40:41], -1, 0
	s_cbranch_scc1 .Lattn_fast2
	v_max_f32_e32 v194, v210, v194
	v_sub_f32_e32 v195, v210, v194
	v_mul_f32_e32 v195, 0x3dd53b94, v195
	v_exp_f32_e32 v213, v195
	v_mov_b32_e32 v210, v194
	s_branch .Lattn_join2
.Lattn_fast2:
	v_mov_b32_e32 v213, 1.0
; __device__ __forceinline__ void partialSM(f32x16& p0, f32x16& p1, float& m_reg, float& mn, float& alpha) {
;   constexpr float C = SCALE * 1.4426950408889634f;
;   float pmax = p0[0];
; #pragma unroll
;   for (int r = 1; r < 16; ++r) pmax = fmaxf(pmax, p0[r]);
; #pragma unroll
;   for (int r = 0; r < 16; ++r) pmax = fmaxf(pmax, p1[r]);
;   { auto rr = __builtin_amdgcn_permlane32_swap(__float_as_uint(pmax), __float_as_uint(pmax), false, false);
;     pmax = fmaxf(__uint_as_float(rr[0]), __uint_as_float(rr[1])); }
;   if (__builtin_expect(__all(pmax - m_reg <= THR / SCALE), 1)) { mn = m_reg; alpha = 1.f; }
;   else { mn = fmaxf(m_reg, pmax); alpha = __builtin_amdgcn_exp2f((m_reg - mn) * C); m_reg = mn; }
;   float mnC = -mn * C;
; #pragma unroll
;   for (int r = 0; r < 16; ++r) p0[r] = fmaf(p0[r], C, mnC);
; #pragma unroll
;   for (int r = 0; r < 16; ++r) p1[r] = fmaf(p1[r], C, mnC);
; #pragma unroll
;   for (int r = 0; r < 16; ++r) p0[r] = __builtin_amdgcn_exp2f(p0[r]);
; }
.Lattn_join2:
	v_mul_f32_e32 v194, 0xbdd53b94, v210
	v_fmamk_f32 v80, v80, 0x3dd53b94, v194
	v_fmamk_f32 v81, v81, 0x3dd53b94, v194
	s_waitcnt lgkmcnt(4)
	v_mfma_f32_32x32x16_bf16 v[32:47], v[152:155], v[240:243], v[32:47]
	ds_read_b64_tr_b16 v[240:241], v231 offset:8192
	ds_read_b64_tr_b16 v[242:243], v231 offset:10240
	v_fmamk_f32 v82, v82, 0x3dd53b94, v194
	v_exp_f32_e32 v225, v80
	v_fmamk_f32 v83, v83, 0x3dd53b94, v194
	v_exp_f32_e32 v228, v81
	v_mfma_f32_32x32x16_bf16 v[48:63], v[152:155], v[248:251], v[48:63]
	ds_read_b64_tr_b16 v[248:249], v231 offset:8704
	ds_read_b64_tr_b16 v[250:251], v231 offset:10752
	v_fmamk_f32 v150, v76, 0x3dd53b94, v194
	v_fmamk_f32 v151, v77, 0x3dd53b94, v194
	v_fmamk_f32 v148, v78, 0x3dd53b94, v194
	v_fmamk_f32 v149, v79, 0x3dd53b94, v194
	v_fmamk_f32 v84, v84, 0x3dd53b94, v194
	s_waitcnt lgkmcnt(4)
	v_mfma_f32_32x32x16_bf16 v[16:31], v[152:155], v[232:235], v[16:31]
	ds_read_b64_tr_b16 v[232:233], v231 offset:9216
	ds_read_b64_tr_b16 v[234:235], v231 offset:11264
	v_exp_f32_e32 v226, v82
	v_fmamk_f32 v85, v85, 0x3dd53b94, v194
	v_exp_f32_e32 v229, v83
	v_fmamk_f32 v86, v86, 0x3dd53b94, v194
	v_mfma_f32_32x32x16_bf16 v[0:15], v[152:155], v[236:239], v[0:15]
	ds_read_b64_tr_b16 v[236:237], v231 offset:9728
	ds_read_b64_tr_b16 v[238:239], v231 offset:11776
	v_exp_f32_e32 v227, v84
	v_fmamk_f32 v87, v87, 0x3dd53b94, v194
	v_exp_f32_e32 v230, v85
	v_fmamk_f32 v154, v72, 0x3dd53b94, v194
	s_waitcnt lgkmcnt(4)
	v_mfma_f32_32x32x16_bf16 v[32:47], v[156:159], v[240:243], v[32:47]
	ds_read_b64_tr_b16 v[240:241], v231 offset:12288
	ds_read_b64_tr_b16 v[242:243], v231 offset:14336
	v_fmamk_f32 v155, v73, 0x3dd53b94, v194
	v_fmamk_f32 v152, v74, 0x3dd53b94, v194
	v_fmamk_f32 v153, v75, 0x3dd53b94, v194
	v_fmamk_f32 v88, v88, 0x3dd53b94, v194
	v_exp_f32_e32 v223, v86
	v_mfma_f32_32x32x16_bf16 v[48:63], v[156:159], v[248:251], v[48:63]
	ds_read_b64_tr_b16 v[248:249], v231 offset:12800
	ds_read_b64_tr_b16 v[250:251], v231 offset:14848
	v_fmamk_f32 v89, v89, 0x3dd53b94, v194
	v_exp_f32_e32 v224, v87
	v_fmamk_f32 v90, v90, 0x3dd53b94, v194
	v_exp_f32_e32 v219, v88
	s_waitcnt lgkmcnt(4)
	v_mfma_f32_32x32x16_bf16 v[16:31], v[156:159], v[232:235], v[16:31]
	ds_read_b64_tr_b16 v[232:233], v231 offset:13312
	ds_read_b64_tr_b16 v[234:235], v231 offset:15360
	v_fmamk_f32 v91, v91, 0x3dd53b94, v194
	v_exp_f32_e32 v221, v89
	v_fmamk_f32 v92, v92, 0x3dd53b94, v194
	v_exp_f32_e32 v220, v90
	v_mfma_f32_32x32x16_bf16 v[0:15], v[156:159], v[236:239], v[0:15]
	ds_read_b64_tr_b16 v[236:237], v231 offset:13824
	ds_read_b64_tr_b16 v[238:239], v231 offset:15872
	v_fmamk_f32 v158, v68, 0x3dd53b94, v194
	v_fmamk_f32 v159, v69, 0x3dd53b94, v194
	v_fmamk_f32 v156, v70, 0x3dd53b94, v194
	v_fmamk_f32 v157, v71, 0x3dd53b94, v194
	v_fmamk_f32 v93, v93, 0x3dd53b94, v194
	s_waitcnt lgkmcnt(4)
	v_mfma_f32_32x32x16_bf16 v[32:47], v[160:163], v[240:243], v[32:47]
	v_exp_f32_e32 v222, v91
	v_fmamk_f32 v94, v94, 0x3dd53b94, v194
	v_exp_f32_e32 v215, v92
	v_fmamk_f32 v95, v95, 0x3dd53b94, v194
	v_mfma_f32_32x32x16_bf16 v[48:63], v[160:163], v[248:251], v[48:63]
	v_exp_f32_e32 v217, v93
	v_exp_f32_e32 v216, v94
	v_exp_f32_e32 v218, v95
	s_waitcnt lgkmcnt(0)
	v_mfma_f32_32x32x16_bf16 v[16:31], v[160:163], v[232:235], v[16:31]
	v_mfma_f32_32x32x16_bf16 v[0:15], v[160:163], v[236:239], v[0:15]
	v_fmamk_f32 v162, v64, 0x3dd53b94, v194
	v_fmamk_f32 v163, v65, 0x3dd53b94, v194
	v_fmamk_f32 v160, v66, 0x3dd53b94, v194
	v_fmamk_f32 v161, v67, 0x3dd53b94, v194
	s_and_b64 vcc, exec, s[40:41]
	s_cbranch_vccnz .Lattn_skip_rs2
	s_and_saveexec_b64 s[18:19], s[38:39]
	ds_write_b32 v175, v213 offset:128
	s_or_b64 exec, exec, s[18:19]
	s_waitcnt lgkmcnt(0)
	v_add_u32_e32 v194, v173, v164
	ds_read_b128 v[232:235], v194 offset:224
	ds_read_b128 v[236:239], v194 offset:192
	ds_read_b128 v[240:243], v194 offset:160
	ds_read_b128 v[248:251], v194 offset:128
	s_waitcnt lgkmcnt(0)
	v_pk_mul_f32 v[44:45], v[44:45], v[232:233]
	v_pk_mul_f32 v[46:47], v[46:47], v[234:235]
	v_pk_mul_f32 v[40:41], v[40:41], v[236:237]
	v_pk_mul_f32 v[42:43], v[42:43], v[238:239]
	v_pk_mul_f32 v[36:37], v[36:37], v[240:241]
	v_pk_mul_f32 v[38:39], v[38:39], v[242:243]
	v_pk_mul_f32 v[32:33], v[32:33], v[248:249]
	v_pk_mul_f32 v[34:35], v[34:35], v[250:251]
	v_pk_mul_f32 v[60:61], v[60:61], v[232:233]
	v_pk_mul_f32 v[62:63], v[62:63], v[234:235]
	v_pk_mul_f32 v[56:57], v[56:57], v[236:237]
	v_pk_mul_f32 v[58:59], v[58:59], v[238:239]
	v_pk_mul_f32 v[52:53], v[52:53], v[240:241]
	v_pk_mul_f32 v[54:55], v[54:55], v[242:243]
	v_pk_mul_f32 v[48:49], v[48:49], v[248:249]
	v_pk_mul_f32 v[50:51], v[50:51], v[250:251]
	v_pk_mul_f32 v[28:29], v[28:29], v[232:233]
	v_pk_mul_f32 v[30:31], v[30:31], v[234:235]
	v_pk_mul_f32 v[24:25], v[24:25], v[236:237]
	v_pk_mul_f32 v[26:27], v[26:27], v[238:239]
	v_pk_mul_f32 v[20:21], v[20:21], v[240:241]
	v_pk_mul_f32 v[22:23], v[22:23], v[242:243]
	v_pk_mul_f32 v[16:17], v[16:17], v[248:249]
	v_pk_mul_f32 v[18:19], v[18:19], v[250:251]
	v_pk_mul_f32 v[12:13], v[12:13], v[232:233]
	v_pk_mul_f32 v[14:15], v[14:15], v[234:235]
	v_pk_mul_f32 v[8:9], v[8:9], v[236:237]
	v_pk_mul_f32 v[10:11], v[10:11], v[238:239]
	v_pk_mul_f32 v[4:5], v[4:5], v[240:241]
	v_pk_mul_f32 v[6:7], v[6:7], v[242:243]
	v_pk_mul_f32 v[0:1], v[0:1], v[248:249]
	v_pk_mul_f32 v[2:3], v[2:3], v[250:251]

; #define SBAR() __builtin_amdgcn_sched_barrier(0)
; __device__ __forceinline__ void qkt(f32x16& p0, f32x16& p1, const char* Ks, const bf16x8* qr, const char* qrl, int r32, int hi) {
;   p0 = f32x16{}; p1 = f32x16{};
; #pragma unroll
;   for (int d0 = 0; d0 < 8; ++d0) { int cb = (d0 * 16 + hi * 8) * 2;
;     bf16x8 b0 = *reinterpret_cast<const bf16x8*>(Ks + KSWZ(r32, cb));
;     bf16x8 b1 = *reinterpret_cast<const bf16x8*>(Ks + KSWZ(32 + r32, cb));
;     p0 = __builtin_amdgcn_mfma_f32_32x32x16_bf16(b0, qr[d0], p0, 0, 0, 0);
;     p1 = __builtin_amdgcn_mfma_f32_32x32x16_bf16(b1, qr[d0], p1, 0, 0, 0); }
; #pragma unroll
;   for (int d0 = 8; d0 < 12; ++d0) { int cb = (d0 * 16 + hi * 8) * 2;
;     bf16x8 b0 = *reinterpret_cast<const bf16x8*>(Ks + KSWZ(r32, cb));
;     bf16x8 b1 = *reinterpret_cast<const bf16x8*>(Ks + KSWZ(32 + r32, cb));
;     bf16x8 qf = *reinterpret_cast<const bf16x8*>(qrl + (((2 * (d0 - 8) + hi) ^ ((r32 >> 1) & 7)) << 4));
;     p0 = __builtin_amdgcn_mfma_f32_32x32x16_bf16(b0, qf, p0, 0, 0, 0);
;     p1 = __builtin_amdgcn_mfma_f32_32x32x16_bf16(b1, qf, p1, 0, 0, 0); }
; }
; __device__ __forceinline__ void attn_unit(const bf16_t* __restrict__ Qb, const bf16_t* __restrict__ Kn, const bf16_t* __restrict__ Vh, const bf16_t* __restrict__ Kr,
;                                           bf16_t* GO, int seq, char* lds, const int tid) {
;     ...
;   { const int bp = bc == 0 ? 2 : bc - 1;
;     SBAR(); qkt(pB0, pB1, K_lds + bc * SHM_K, qr, qrl, r32, hi);
;     finishSM(pA0, pA1, alA, l_reg, pa0, pa1, pa2, pa3); SBAR();
.LBB0_1163:
	v_add_u32_e32 v199, 0xffff7000, v199
	v_add_u32_e32 v205, 0xffff7000, v205
	v_add_u32_e32 v206, 0xffff7000, v206
	v_add_u32_e32 v208, 0xffff7000, v208
	v_add_u32_e32 v207, 0xffff7000, v207
	v_add_u32_e32 v204, 0xffff7000, v204
	v_add_u32_e32 v203, 0xffff7000, v203
	v_add_u32_e32 v200, 0xffff7000, v200
	v_add_u32_e32 v191, 0xffff7000, v191
	v_add_u32_e32 v198, 0xffff7000, v198
	v_add_u32_e32 v187, 0xffff7000, v187
	v_add_u32_e32 v188, 0xffff7000, v188
	v_add_u32_e32 v202, 0xffff7000, v202
	v_add_u32_e32 v201, 0xffff7000, v201
	v_add_u32_e32 v189, 0xffff7000, v189
	v_add_u32_e32 v190, 0xffff7000, v190
	v_add_u32_e32 v185, 0xffff7000, v185
	v_add_u32_e32 v186, 0xffff7000, v186
	v_add_u32_e32 v68, s34, v199
	ds_read_b128 v[64:67], v68 offset:49152
	ds_read_b128 v[68:71], v68 offset:61440
	s_waitcnt vmcnt(0)
	v_add_u32_e32 v128, s34, v205
	s_waitcnt lgkmcnt(1)
	v_mfma_f32_32x32x16_bf16 v[80:95], v[64:67], v[124:127], 0
	s_waitcnt lgkmcnt(0)
	v_mfma_f32_32x32x16_bf16 v[64:79], v[68:71], v[124:127], 0
	ds_read_b128 v[124:127], v128 offset:49152
	ds_read_b128 v[128:131], v128 offset:61440
	s_waitcnt lgkmcnt(1)
	v_mfma_f32_32x32x16_bf16 v[80:95], v[124:127], v[120:123], v[80:95]
	v_add_u32_e32 v124, s34, v206
	s_waitcnt lgkmcnt(0)
	v_mfma_f32_32x32x16_bf16 v[64:79], v[128:131], v[120:123], v[64:79]
	ds_read_b128 v[120:123], v124 offset:49152
	ds_read_b128 v[124:127], v124 offset:61440
	s_waitcnt lgkmcnt(1)
	v_mfma_f32_32x32x16_bf16 v[80:95], v[120:123], v[116:119], v[80:95]
	v_add_u32_e32 v120, s34, v208
	s_waitcnt lgkmcnt(0)
	v_mfma_f32_32x32x16_bf16 v[64:79], v[124:127], v[116:119], v[64:79]
	ds_read_b128 v[116:119], v120 offset:49152
	ds_read_b128 v[120:123], v120 offset:61440
	s_waitcnt lgkmcnt(1)
	v_mfma_f32_32x32x16_bf16 v[80:95], v[116:119], v[112:115], v[80:95]
	v_add_u32_e32 v116, s34, v207
	s_waitcnt lgkmcnt(0)
	v_mfma_f32_32x32x16_bf16 v[64:79], v[120:123], v[112:115], v[64:79]
	ds_read_b128 v[112:115], v116 offset:49152
	ds_read_b128 v[116:119], v116 offset:61440
	v_exp_f32_e32 v120, v148
	v_exp_f32_e32 v121, v149
	s_waitcnt lgkmcnt(1)
	v_mfma_f32_32x32x16_bf16 v[80:95], v[112:115], v[108:111], v[80:95]
	v_add_u32_e32 v112, s34, v204
	s_waitcnt lgkmcnt(0)
	v_mfma_f32_32x32x16_bf16 v[64:79], v[116:119], v[108:111], v[64:79]
	ds_read_b128 v[108:111], v112 offset:49152
	ds_read_b128 v[112:115], v112 offset:61440
	v_exp_f32_e32 v116, v152
	v_exp_f32_e32 v117, v153
	v_exp_f32_e32 v118, v150
	v_exp_f32_e32 v119, v151
	s_waitcnt lgkmcnt(1)
	v_mfma_f32_32x32x16_bf16 v[80:95], v[108:111], v[104:107], v[80:95]
	v_add_u32_e32 v108, s34, v203
	s_waitcnt lgkmcnt(0)
	v_mfma_f32_32x32x16_bf16 v[64:79], v[112:115], v[104:107], v[64:79]
	ds_read_b128 v[104:107], v108 offset:49152
	ds_read_b128 v[108:111], v108 offset:61440
	v_exp_f32_e32 v112, v156
	v_exp_f32_e32 v113, v157
	v_exp_f32_e32 v114, v154
	v_exp_f32_e32 v115, v155
	s_waitcnt lgkmcnt(1)
	v_mfma_f32_32x32x16_bf16 v[80:95], v[104:107], v[100:103], v[80:95]
	v_add_u32_e32 v104, s34, v200
	s_waitcnt lgkmcnt(0)
	v_mfma_f32_32x32x16_bf16 v[64:79], v[108:111], v[100:103], v[64:79]
	ds_read_b128 v[100:103], v104 offset:49152
	ds_read_b128 v[104:107], v104 offset:61440
	v_exp_f32_e32 v108, v160
	v_exp_f32_e32 v109, v161
	v_exp_f32_e32 v110, v158
	v_exp_f32_e32 v111, v159
	s_waitcnt lgkmcnt(1)
	v_mfma_f32_32x32x16_bf16 v[80:95], v[100:103], v[96:99], v[80:95]
	v_add_u32_e32 v100, s34, v202
	s_waitcnt lgkmcnt(0)
	v_mfma_f32_32x32x16_bf16 v[64:79], v[104:107], v[96:99], v[64:79]
	v_add_u32_e32 v96, s34, v191
	ds_read_b128 v[96:99], v96 offset:49152
	ds_read_b128 v[100:103], v100 offset:61440
	ds_read_b128 v[104:107], v182
	s_waitcnt lgkmcnt(0)
	v_mfma_f32_32x32x16_bf16 v[80:95], v[96:99], v[104:107], v[80:95]
	v_add_u32_e32 v96, s34, v198
	ds_read_b128 v[96:99], v96 offset:49152
	v_mfma_f32_32x32x16_bf16 v[64:79], v[100:103], v[104:107], v[64:79]
	v_add_u32_e32 v100, s34, v201
	ds_read_b128 v[100:103], v100 offset:61440
	ds_read_b128 v[104:107], v181
	s_waitcnt lgkmcnt(0)
	v_mfma_f32_32x32x16_bf16 v[80:95], v[96:99], v[104:107], v[80:95]
	v_add_u32_e32 v96, s34, v187
	ds_read_b128 v[96:99], v96 offset:49152
	v_mfma_f32_32x32x16_bf16 v[64:79], v[100:103], v[104:107], v[64:79]
	v_add_u32_e32 v100, s34, v189
	ds_read_b128 v[100:103], v100 offset:61440
	ds_read_b128 v[104:107], v179
	s_waitcnt lgkmcnt(0)
	v_mfma_f32_32x32x16_bf16 v[80:95], v[96:99], v[104:107], v[80:95]
	v_add_u32_e32 v96, s34, v188
	ds_read_b128 v[96:99], v96 offset:49152
	v_mfma_f32_32x32x16_bf16 v[64:79], v[100:103], v[104:107], v[64:79]
	v_add_u32_e32 v100, s34, v190
	ds_read_b128 v[100:103], v100 offset:61440
	ds_read_b128 v[104:107], v177
	s_waitcnt lgkmcnt(0)
; #define SBAR() __builtin_amdgcn_sched_barrier(0)
; #define RESC(a) do { if (__any((a) < 1.f)) { if (hi == 0) al_l[r32] = (a); asm volatile("s_waitcnt lgkmcnt(0)" ::: "memory"); \
;     _Pragma("unroll") for (int d = 0; d < 4; ++d) _Pragma("unroll") for (int r = 0; r < 16; ++r) o[d][r] *= al_l[crow(r, hi)]; } } while (0)
; __device__ __forceinline__ void finishSM(f32x16& p0, f32x16& p1, float alpha, float& l_reg, bf16x8& pa0, bf16x8& pa1, bf16x8& pa2, bf16x8& pa3) {
; #pragma unroll
;   for (int r = 0; r < 16; ++r) p1[r] = __builtin_amdgcn_exp2f(p1[r]);
;   float ps = 0;
; #pragma unroll
;   for (int r = 0; r < 16; ++r) ps += p0[r];
; #pragma unroll
;   for (int r = 0; r < 16; ++r) ps += p1[r];
;   { auto rr = __builtin_amdgcn_permlane32_swap(__float_as_uint(ps), __float_as_uint(ps), false, false);
;     ps = __uint_as_float(rr[0]) + __uint_as_float(rr[1]); }
;   l_reg = l_reg * alpha + ps;
;     ...
;   PK4(p0, 0, pa0); PK4(p0, 8, pa1); PK4(p1, 0, pa2); PK4(p1, 8, pa3);
;     ...
; }
; __device__ __forceinline__ void attn_unit(const bf16_t* __restrict__ Qb, const bf16_t* __restrict__ Kn, const bf16_t* __restrict__ Vh, const bf16_t* __restrict__ Kr,
;                                           bf16_t* GO, int seq, char* lds, const int tid) {
;     ...
;     finishSM(pA0, pA1, alA, l_reg, pa0, pa1, pa2, pa3); SBAR();
;     pv_d0(o, vb0 + bp * SHM_V, pa0, pa1, pa2, pa3); partialSM(pB0, pB1, m_reg, mnB, alB);
;     RESC(alB);
	v_mfma_f32_32x32x16_bf16 v[80:95], v[96:99], v[104:107], v[80:95]
	v_add_f32_e32 v96, 0, v225
	v_add_f32_e32 v96, v228, v96
	v_add_f32_e32 v96, v226, v96
	v_add_f32_e32 v96, v229, v96
	v_add_f32_e32 v96, v227, v96
	v_add_f32_e32 v96, v230, v96
	v_add_f32_e32 v96, v223, v96
	v_add_f32_e32 v96, v224, v96
	v_add_f32_e32 v96, v219, v96
	v_add_f32_e32 v96, v221, v96
	v_add_f32_e32 v96, v220, v96
	v_add_f32_e32 v96, v222, v96
	v_mfma_f32_32x32x16_bf16 v[64:79], v[100:103], v[104:107], v[64:79]
	v_exp_f32_e32 v106, v162
	v_add_f32_e32 v96, v215, v96
	v_exp_f32_e32 v107, v163
	v_add_f32_e32 v96, v217, v96
	v_add_f32_e32 v96, v216, v96
	v_add_f32_e32 v96, v218, v96
	v_add_f32_e32 v96, v106, v96
	v_add_f32_e32 v96, v107, v96
	v_add_f32_e32 v96, v108, v96
	v_add_f32_e32 v96, v109, v96
	v_add_f32_e32 v96, v110, v96
	v_add_f32_e32 v96, v111, v96
	v_add_f32_e32 v96, v112, v96
	v_add_f32_e32 v96, v113, v96
	v_add_f32_e32 v96, v114, v96
	v_add_f32_e32 v96, v115, v96
	v_add_f32_e32 v96, v116, v96
	v_add_f32_e32 v96, v117, v96
	v_add_f32_e32 v96, v118, v96
	v_add_f32_e32 v96, v119, v96
	v_add_f32_e32 v96, v120, v96
	v_add_f32_e32 v100, v121, v96
	v_mov_b32_e32 v101, v100
	v_cvt_pk_bf16_f32 v96, v225, v228
	v_cvt_pk_bf16_f32 v97, v226, v229
	v_cvt_pk_bf16_f32 v98, v227, v230
	v_cvt_pk_bf16_f32 v99, v223, v224
	s_nop 1
	v_permlane32_swap_b32_e32 v100, v101
	v_cvt_pk_bf16_f32 v102, v219, v221
	v_cvt_pk_bf16_f32 v103, v220, v222
	v_cvt_pk_bf16_f32 v104, v215, v217
	v_cvt_pk_bf16_f32 v105, v216, v218
	v_cvt_pk_bf16_f32 v106, v106, v107
	v_cvt_pk_bf16_f32 v107, v108, v109
	v_cvt_pk_bf16_f32 v108, v110, v111
	v_cvt_pk_bf16_f32 v109, v112, v113
	v_cvt_pk_bf16_f32 v110, v114, v115
	v_cvt_pk_bf16_f32 v111, v116, v117
	v_cvt_pk_bf16_f32 v112, v118, v119
	v_cvt_pk_bf16_f32 v113, v120, v121
	s_nop 0
	s_addk_i32 s31, 0xc000
	s_cmp_lg_u32 s30, 0
	s_cselect_b32 s18, s31, 0x8000
	v_add_u32_e32 v130, s18, v178
	ds_read_b64_tr_b16 v[114:115], v130 offset:0
	ds_read_b64_tr_b16 v[116:117], v130 offset:0x800
	ds_read_b64_tr_b16 v[118:119], v130 offset:0x1000
	ds_read_b64_tr_b16 v[120:121], v130 offset:0x1800
	ds_read_b64_tr_b16 v[122:123], v130 offset:0x2000
	ds_read_b64_tr_b16 v[124:125], v130 offset:0x2800
	ds_read_b64_tr_b16 v[126:127], v130 offset:0x3000
	ds_read_b64_tr_b16 v[128:129], v130 offset:0x3800
	s_waitcnt lgkmcnt(0)
	s_nop 0
	v_mfma_f32_32x32x16_bf16 v[32:47], v[96:99], v[114:117], v[32:47]
	ds_read_b64_tr_b16 v[114:115], v130 offset:0x200
	ds_read_b64_tr_b16 v[116:117], v130 offset:0xa00
	v_mfma_f32_32x32x16_bf16 v[32:47], v[102:105], v[118:121], v[32:47]
	ds_read_b64_tr_b16 v[118:119], v130 offset:0x1200
	ds_read_b64_tr_b16 v[120:121], v130 offset:0x1a00
	v_mfma_f32_32x32x16_bf16 v[32:47], v[106:109], v[122:125], v[32:47]
	ds_read_b64_tr_b16 v[122:123], v130 offset:0x2200
	ds_read_b64_tr_b16 v[124:125], v130 offset:0x2a00
	v_mfma_f32_32x32x16_bf16 v[32:47], v[110:113], v[126:129], v[32:47]
	ds_read_b64_tr_b16 v[126:127], v130 offset:0x3200
	ds_read_b64_tr_b16 v[128:129], v130 offset:0x3a00
	s_waitcnt lgkmcnt(0)
	v_mfma_f32_32x32x16_bf16 v[48:63], v[96:99], v[114:117], v[48:63]
	ds_read_b64_tr_b16 v[114:115], v130 offset:0x400
	ds_read_b64_tr_b16 v[116:117], v130 offset:0xc00
	v_mfma_f32_32x32x16_bf16 v[48:63], v[102:105], v[118:121], v[48:63]
	ds_read_b64_tr_b16 v[118:119], v130 offset:0x1400
	ds_read_b64_tr_b16 v[120:121], v130 offset:0x1c00
	v_mfma_f32_32x32x16_bf16 v[48:63], v[106:109], v[122:125], v[48:63]
	ds_read_b64_tr_b16 v[122:123], v130 offset:0x2400
	ds_read_b64_tr_b16 v[124:125], v130 offset:0x2c00
	v_mfma_f32_32x32x16_bf16 v[48:63], v[110:113], v[126:129], v[48:63]
	ds_read_b64_tr_b16 v[126:127], v130 offset:0x3400
	ds_read_b64_tr_b16 v[128:129], v130 offset:0x3c00
	s_waitcnt lgkmcnt(0)
	v_mfma_f32_32x32x16_bf16 v[16:31], v[96:99], v[114:117], v[16:31]
	ds_read_b64_tr_b16 v[114:115], v130 offset:0x600
	ds_read_b64_tr_b16 v[116:117], v130 offset:0xe00
	v_mfma_f32_32x32x16_bf16 v[16:31], v[102:105], v[118:121], v[16:31]
	ds_read_b64_tr_b16 v[118:119], v130 offset:0x1600
	ds_read_b64_tr_b16 v[120:121], v130 offset:0x1e00
	v_mfma_f32_32x32x16_bf16 v[16:31], v[106:109], v[122:125], v[16:31]
	ds_read_b64_tr_b16 v[122:123], v130 offset:0x2600
	ds_read_b64_tr_b16 v[124:125], v130 offset:0x2e00
	v_mfma_f32_32x32x16_bf16 v[16:31], v[110:113], v[126:129], v[16:31]
	ds_read_b64_tr_b16 v[126:127], v130 offset:0x3600
	ds_read_b64_tr_b16 v[128:129], v130 offset:0x3e00
	s_waitcnt lgkmcnt(0)
	v_mfma_f32_32x32x16_bf16 v[0:15], v[96:99], v[114:117], v[0:15]
	v_max_f32_e32 v96, v81, v81
	v_max_f32_e32 v97, v80, v80
	v_max_f32_e32 v96, v97, v96
	v_max3_f32 v96, v96, v82, v83
	v_max3_f32 v96, v96, v84, v85
	v_max3_f32 v96, v96, v86, v87
	v_max3_f32 v96, v96, v88, v89
	v_max3_f32 v96, v96, v90, v91
	v_max3_f32 v96, v96, v92, v93
	v_mfma_f32_32x32x16_bf16 v[0:15], v[102:105], v[118:121], v[0:15]
	v_max3_f32 v96, v96, v94, v95
	v_max3_f32 v96, v96, v64, v65
	v_max3_f32 v96, v96, v66, v67
	v_max3_f32 v96, v96, v68, v69
	v_max3_f32 v96, v96, v70, v71
	v_max3_f32 v96, v96, v72, v73
	v_max3_f32 v96, v96, v74, v75
	v_max3_f32 v96, v96, v76, v77
	v_mfma_f32_32x32x16_bf16 v[0:15], v[106:109], v[122:125], v[0:15]
	v_max3_f32 v96, v96, v78, v79
	v_mov_b32_e32 v97, v96
	s_nop 1
	v_permlane32_swap_b32_e32 v96, v97
	v_max_f32_e32 v97, v97, v97
	v_max_f32_e32 v96, v96, v96
	v_max_f32_e32 v96, v96, v97
	v_sub_f32_e32 v97, v96, v210
	v_cmp_ge_f32_e32 vcc, s15, v97
	v_max_f32_e32 v97, v210, v210
	v_max_f32_e32 v97, v97, v96
	v_mfma_f32_32x32x16_bf16 v[0:15], v[110:113], v[126:129], v[0:15]
	v_sub_f32_e32 v96, v210, v97
	v_mul_f32_e32 v96, 0x3dd53b94, v96
	v_exp_f32_e32 v96, v96
	s_cmp_eq_u64 vcc, exec
	s_cselect_b64 s[40:41], -1, 0
	v_cndmask_b32_e64 v96, v96, 1.0, s[40:41]
	v_cmp_gt_f32_e32 vcc, 1.0, v96
	s_cbranch_vccz .LBB0_1167
; #define RESC(a) do { if (__any((a) < 1.f)) { if (hi == 0) al_l[r32] = (a); asm volatile("s_waitcnt lgkmcnt(0)" ::: "memory"); \
;     _Pragma("unroll") for (int d = 0; d < 4; ++d) _Pragma("unroll") for (int r = 0; r < 16; ++r) o[d][r] *= al_l[crow(r, hi)]; } } while (0)
; __device__ __forceinline__ void attn_unit(const bf16_t* __restrict__ Qb, const bf16_t* __restrict__ Kn, const bf16_t* __restrict__ Vh, const bf16_t* __restrict__ Kr,
;                                           bf16_t* GO, int seq, char* lds, const int tid) {
;     ...
;     RESC(alB);
	s_and_saveexec_b64 s[18:19], s[38:39]
	ds_write_b32 v175, v96 offset:128
	s_or_b64 exec, exec, s[18:19]
	s_waitcnt lgkmcnt(0)
	v_add_u32_e32 v98, v173, v164
	ds_read_b128 v[102:105], v98 offset:224
	ds_read_b128 v[106:109], v98 offset:192
	ds_read_b128 v[110:113], v98 offset:160
	ds_read_b128 v[114:117], v98 offset:128
	s_waitcnt lgkmcnt(3)
	v_pk_mul_f32 v[44:45], v[44:45], v[102:103]
	s_waitcnt lgkmcnt(2)
	v_pk_mul_f32 v[40:41], v[40:41], v[106:107]
	s_waitcnt lgkmcnt(1)
	v_pk_mul_f32 v[36:37], v[36:37], v[110:111]
	v_pk_mul_f32 v[46:47], v[46:47], v[104:105]
	v_pk_mul_f32 v[42:43], v[42:43], v[108:109]
	v_pk_mul_f32 v[38:39], v[38:39], v[112:113]
	s_waitcnt lgkmcnt(0)
	v_pk_mul_f32 v[34:35], v[34:35], v[116:117]
	v_pk_mul_f32 v[32:33], v[32:33], v[114:115]
	v_pk_mul_f32 v[60:61], v[60:61], v[102:103]
	v_pk_mul_f32 v[56:57], v[56:57], v[106:107]
	v_pk_mul_f32 v[52:53], v[52:53], v[110:111]
	v_pk_mul_f32 v[62:63], v[62:63], v[104:105]
	v_pk_mul_f32 v[58:59], v[58:59], v[108:109]
	v_pk_mul_f32 v[54:55], v[54:55], v[112:113]
	v_pk_mul_f32 v[50:51], v[50:51], v[116:117]
	v_pk_mul_f32 v[48:49], v[48:49], v[114:115]
	v_pk_mul_f32 v[28:29], v[28:29], v[102:103]
	v_pk_mul_f32 v[24:25], v[24:25], v[106:107]
	v_pk_mul_f32 v[20:21], v[20:21], v[110:111]
	v_pk_mul_f32 v[30:31], v[30:31], v[104:105]
	v_pk_mul_f32 v[26:27], v[26:27], v[108:109]
	v_pk_mul_f32 v[22:23], v[22:23], v[112:113]
	v_pk_mul_f32 v[18:19], v[18:19], v[116:117]
	v_pk_mul_f32 v[16:17], v[16:17], v[114:115]
	v_pk_mul_f32 v[12:13], v[12:13], v[102:103]
	v_pk_mul_f32 v[8:9], v[8:9], v[106:107]
	v_pk_mul_f32 v[4:5], v[4:5], v[110:111]
	v_pk_mul_f32 v[14:15], v[14:15], v[104:105]
	v_pk_mul_f32 v[10:11], v[10:11], v[108:109]
	v_pk_mul_f32 v[6:7], v[6:7], v[112:113]
	v_pk_mul_f32 v[2:3], v[2:3], v[116:117]
	v_pk_mul_f32 v[0:1], v[0:1], v[114:115]
; #define SBAR() __builtin_amdgcn_sched_barrier(0)
; __device__ __forceinline__ void partialSM(f32x16& p0, f32x16& p1, float& m_reg, float& mn, float& alpha) {
;     ...
;   float mnC = -mn * C;
; #pragma unroll
;   for (int r = 0; r < 16; ++r) p0[r] = fmaf(p0[r], C, mnC);
; #pragma unroll
;   for (int r = 0; r < 16; ++r) p1[r] = fmaf(p1[r], C, mnC);
; #pragma unroll
;   for (int r = 0; r < 16; ++r) p0[r] = __builtin_amdgcn_exp2f(p0[r]);
; }
; __device__ __forceinline__ void finishSM(f32x16& p0, f32x16& p1, float alpha, float& l_reg, bf16x8& pa0, bf16x8& pa1, bf16x8& pa2, bf16x8& pa3) {
; #pragma unroll
;   for (int r = 0; r < 16; ++r) p1[r] = __builtin_amdgcn_exp2f(p1[r]);
;   float ps = 0;
; #pragma unroll
;   for (int r = 0; r < 16; ++r) ps += p0[r];
; #pragma unroll
;   for (int r = 0; r < 16; ++r) ps += p1[r];
;   { auto rr = __builtin_amdgcn_permlane32_swap(__float_as_uint(ps), __float_as_uint(ps), false, false);
;     ps = __uint_as_float(rr[0]) + __uint_as_float(rr[1]); }
;   l_reg = l_reg * alpha + ps;
;     ...
;   PK4(p0, 0, pa0); PK4(p0, 8, pa1); PK4(p1, 0, pa2); PK4(p1, 8, pa3);
;     ...
; }
; __device__ __forceinline__ void attn_unit(const bf16_t* __restrict__ Qb, const bf16_t* __restrict__ Kn, const bf16_t* __restrict__ Vh, const bf16_t* __restrict__ Kr,
;                                           bf16_t* GO, int seq, char* lds, const int tid) {
;     ...
;     finishSM(pB0, pB1, alB, l_reg, pa0, pa1, pa2, pa3); SBAR();
;     pv_d0(o, vb0 + bc * SHM_V, pa0, pa1, pa2, pa3); }
;     ...
;   if (hi == 0) li_l[r32] = l_reg; asm volatile("s_waitcnt lgkmcnt(0)" ::: "memory");
.LBB0_1167:
	v_cndmask_b32_e64 v97, v97, v210, s[40:41]
	v_mul_f32_e32 v97, 0xbdd53b94, v97
	v_fmamk_f32 v80, v80, 0x3dd53b94, v97
	v_fmamk_f32 v81, v81, 0x3dd53b94, v97
	v_fmamk_f32 v82, v82, 0x3dd53b94, v97
	v_fmamk_f32 v83, v83, 0x3dd53b94, v97
	v_fmamk_f32 v84, v84, 0x3dd53b94, v97
	v_fmamk_f32 v85, v85, 0x3dd53b94, v97
	v_fmamk_f32 v86, v86, 0x3dd53b94, v97
	v_fmamk_f32 v87, v87, 0x3dd53b94, v97
	v_fmamk_f32 v88, v88, 0x3dd53b94, v97
	v_fmamk_f32 v89, v89, 0x3dd53b94, v97
	v_fmamk_f32 v90, v90, 0x3dd53b94, v97
	v_fmamk_f32 v91, v91, 0x3dd53b94, v97
	v_fmamk_f32 v92, v92, 0x3dd53b94, v97
	v_fmamk_f32 v93, v93, 0x3dd53b94, v97
	v_fmamk_f32 v94, v94, 0x3dd53b94, v97
	v_fmamk_f32 v95, v95, 0x3dd53b94, v97
	v_fmamk_f32 v64, v64, 0x3dd53b94, v97
	v_fmamk_f32 v65, v65, 0x3dd53b94, v97
	v_fmamk_f32 v66, v66, 0x3dd53b94, v97
	v_fmamk_f32 v67, v67, 0x3dd53b94, v97
	v_fmamk_f32 v68, v68, 0x3dd53b94, v97
	v_fmamk_f32 v69, v69, 0x3dd53b94, v97
	v_fmamk_f32 v70, v70, 0x3dd53b94, v97
	v_fmamk_f32 v71, v71, 0x3dd53b94, v97
	v_fmamk_f32 v72, v72, 0x3dd53b94, v97
	v_fmamk_f32 v73, v73, 0x3dd53b94, v97
	v_fmamk_f32 v74, v74, 0x3dd53b94, v97
	v_fmamk_f32 v75, v75, 0x3dd53b94, v97
	v_fmamk_f32 v76, v76, 0x3dd53b94, v97
	v_fmamk_f32 v77, v77, 0x3dd53b94, v97
	v_fmamk_f32 v78, v78, 0x3dd53b94, v97
	v_fmac_f32_e32 v97, 0x3dd53b94, v79
	v_exp_f32_e32 v79, v80
	v_exp_f32_e32 v80, v81
	v_exp_f32_e32 v81, v82
	v_exp_f32_e32 v82, v83
	v_exp_f32_e32 v83, v84
	v_exp_f32_e32 v84, v85
	v_exp_f32_e32 v85, v86
	v_exp_f32_e32 v86, v87
	v_exp_f32_e32 v87, v88
	v_exp_f32_e32 v88, v89
	v_exp_f32_e32 v89, v90
	v_exp_f32_e32 v90, v91
	v_exp_f32_e32 v91, v92
	v_exp_f32_e32 v92, v93
	v_exp_f32_e32 v93, v94
	v_exp_f32_e32 v94, v95
	v_exp_f32_e32 v95, v64
	v_add_f32_e32 v64, 0, v79
	v_add_f32_e32 v64, v80, v64
	v_add_f32_e32 v64, v81, v64
	v_add_f32_e32 v64, v82, v64
	v_add_f32_e32 v64, v83, v64
	v_add_f32_e32 v64, v84, v64
	v_add_f32_e32 v64, v85, v64
	v_add_f32_e32 v64, v86, v64
	v_add_f32_e32 v64, v87, v64
	v_add_f32_e32 v64, v88, v64
	v_add_f32_e32 v64, v89, v64
	v_add_f32_e32 v64, v90, v64
	v_add_f32_e32 v64, v91, v64
	v_exp_f32_e32 v98, v65
	v_add_f32_e32 v64, v92, v64
	v_exp_f32_e32 v99, v66
	v_add_f32_e32 v64, v93, v64
	v_exp_f32_e32 v102, v67
	v_add_f32_e32 v64, v94, v64
	v_exp_f32_e32 v103, v68
	v_add_f32_e32 v64, v95, v64
	v_exp_f32_e32 v104, v69
	v_add_f32_e32 v64, v98, v64
	v_exp_f32_e32 v105, v70
	v_add_f32_e32 v64, v99, v64
	v_exp_f32_e32 v106, v71
	v_add_f32_e32 v64, v102, v64
	v_exp_f32_e32 v107, v72
	v_add_f32_e32 v64, v103, v64
	v_exp_f32_e32 v108, v73
	v_add_f32_e32 v64, v104, v64
	v_exp_f32_e32 v109, v74
	v_add_f32_e32 v64, v105, v64
	v_exp_f32_e32 v110, v75
	v_add_f32_e32 v64, v106, v64
	v_exp_f32_e32 v111, v76
	v_add_f32_e32 v64, v107, v64
	v_exp_f32_e32 v112, v77
	v_add_f32_e32 v64, v108, v64
	v_exp_f32_e32 v113, v78
	v_add_f32_e32 v64, v109, v64
	v_exp_f32_e32 v97, v97
	v_add_f32_e32 v64, v110, v64
	v_add_f32_e32 v64, v111, v64
	v_add_f32_e32 v64, v112, v64
	v_add_f32_e32 v64, v113, v64
	v_add_f32_e32 v64, v97, v64
	v_mov_b32_e32 v65, v64
	s_nop 1
	v_permlane32_swap_b32_e32 v64, v65
	v_cvt_pk_bf16_f32 v66, v79, v80
	v_cvt_pk_bf16_f32 v67, v81, v82
	v_cvt_pk_bf16_f32 v68, v83, v84
	v_cvt_pk_bf16_f32 v69, v85, v86
	v_cvt_pk_bf16_f32 v70, v87, v88
	v_cvt_pk_bf16_f32 v71, v89, v90
	v_cvt_pk_bf16_f32 v72, v91, v92
	v_cvt_pk_bf16_f32 v73, v93, v94
	v_cvt_pk_bf16_f32 v74, v95, v98
	v_cvt_pk_bf16_f32 v75, v99, v102
	v_cvt_pk_bf16_f32 v76, v103, v104
	v_cvt_pk_bf16_f32 v77, v105, v106
	v_cvt_pk_bf16_f32 v78, v107, v108
	v_cvt_pk_bf16_f32 v79, v109, v110
	v_cvt_pk_bf16_f32 v80, v111, v112
	v_cvt_pk_bf16_f32 v81, v113, v97
	s_nop 0
	ds_read_b64_tr_b16 v[82:83], v180 offset:0
	ds_read_b64_tr_b16 v[84:85], v180 offset:0x800
	ds_read_b64_tr_b16 v[86:87], v180 offset:0x1000
	ds_read_b64_tr_b16 v[88:89], v180 offset:0x1800
	ds_read_b64_tr_b16 v[90:91], v180 offset:0x2000
	ds_read_b64_tr_b16 v[92:93], v180 offset:0x2800
	ds_read_b64_tr_b16 v[102:103], v180 offset:0x3000
	ds_read_b64_tr_b16 v[104:105], v180 offset:0x3800
	s_waitcnt lgkmcnt(0)
	s_nop 0
	v_mfma_f32_32x32x16_bf16 v[32:47], v[66:69], v[82:85], v[32:47]
	ds_read_b64_tr_b16 v[82:83], v180 offset:0x200
	ds_read_b64_tr_b16 v[84:85], v180 offset:0xa00
	v_mfma_f32_32x32x16_bf16 v[32:47], v[70:73], v[86:89], v[32:47]
	ds_read_b64_tr_b16 v[86:87], v180 offset:0x1200
	ds_read_b64_tr_b16 v[88:89], v180 offset:0x1a00
	v_mfma_f32_32x32x16_bf16 v[32:47], v[74:77], v[90:93], v[32:47]
	ds_read_b64_tr_b16 v[90:91], v180 offset:0x2200
	ds_read_b64_tr_b16 v[92:93], v180 offset:0x2a00
	v_mfma_f32_32x32x16_bf16 v[32:47], v[78:81], v[102:105], v[32:47]
	ds_read_b64_tr_b16 v[102:103], v180 offset:0x3200
	ds_read_b64_tr_b16 v[104:105], v180 offset:0x3a00
	s_waitcnt lgkmcnt(0)
	v_mfma_f32_32x32x16_bf16 v[48:63], v[66:69], v[82:85], v[48:63]
	ds_read_b64_tr_b16 v[82:83], v180 offset:0x400
	ds_read_b64_tr_b16 v[84:85], v180 offset:0xc00
	v_mfma_f32_32x32x16_bf16 v[48:63], v[70:73], v[86:89], v[48:63]
	ds_read_b64_tr_b16 v[86:87], v180 offset:0x1400
	ds_read_b64_tr_b16 v[88:89], v180 offset:0x1c00
	v_mfma_f32_32x32x16_bf16 v[48:63], v[74:77], v[90:93], v[48:63]
	ds_read_b64_tr_b16 v[90:91], v180 offset:0x2400
	ds_read_b64_tr_b16 v[92:93], v180 offset:0x2c00
	v_mfma_f32_32x32x16_bf16 v[48:63], v[78:81], v[102:105], v[48:63]
	ds_read_b64_tr_b16 v[102:103], v180 offset:0x3400
	ds_read_b64_tr_b16 v[104:105], v180 offset:0x3c00
	s_waitcnt lgkmcnt(0)
	v_mfma_f32_32x32x16_bf16 v[16:31], v[66:69], v[82:85], v[16:31]
	ds_read_b64_tr_b16 v[82:83], v180 offset:0x600
	ds_read_b64_tr_b16 v[84:85], v180 offset:0xe00
	v_mfma_f32_32x32x16_bf16 v[16:31], v[70:73], v[86:89], v[16:31]
	ds_read_b64_tr_b16 v[86:87], v180 offset:0x1600
	ds_read_b64_tr_b16 v[88:89], v180 offset:0x1e00
	v_mfma_f32_32x32x16_bf16 v[16:31], v[74:77], v[90:93], v[16:31]
	ds_read_b64_tr_b16 v[90:91], v180 offset:0x2600
	ds_read_b64_tr_b16 v[92:93], v180 offset:0x2e00
	v_mfma_f32_32x32x16_bf16 v[16:31], v[78:81], v[102:105], v[16:31]
	ds_read_b64_tr_b16 v[102:103], v180 offset:0x3600
	ds_read_b64_tr_b16 v[104:105], v180 offset:0x3e00
	s_waitcnt lgkmcnt(0)
	v_mfma_f32_32x32x16_bf16 v[0:15], v[66:69], v[82:85], v[0:15]
	v_mfma_f32_32x32x16_bf16 v[0:15], v[70:73], v[86:89], v[0:15]
	v_mfma_f32_32x32x16_bf16 v[0:15], v[74:77], v[90:93], v[0:15]
	v_mfma_f32_32x32x16_bf16 v[0:15], v[78:81], v[102:105], v[0:15]
	s_and_saveexec_b64 s[18:19], s[38:39]
	s_cbranch_execz .LBB0_1133
	v_add_f32_e32 v66, v100, v101
	v_fmac_f32_e32 v66, v176, v213
	v_add_f32_e32 v64, v64, v65
	v_fmac_f32_e32 v64, v66, v96
	ds_write_b32 v175, v64
	s_branch .LBB0_1133
